# all s_setprio removed from the five GEMM K-loops (both wave halves at equal priority)
# speedup vs baseline: 1.0102x; 1.0065x over previous
; #define PG8_STAGE(bufoff, gbase, voff) do { _Pragma("unroll") for (int _i = 0; _i < 2; ++_i) \
;         __builtin_amdgcn_global_load_lds((const unsigned*)((const char*)(gbase) + (voff)[_i]), (PG8_LAS unsigned*)(lds + (bufoff) + ldsw + _i * 8192), 16, 0, 0); } while (0)
; #define PG8_LDA(dst, b, h) do { _Pragma("unroll") for (int m = 0; m < 4; ++m) _Pragma("unroll") for (int k = 0; k < 2; ++k) dst[m][k] = *(const PG8_LAS bf16x8*)(lds + PG8_SA(b, h) + aoff + m * 2048 + k * 1024); } while (0)
; #define PG8_LDB(dst, b, h) do { _Pragma("unroll") for (int n = 0; n < 2; ++n) _Pragma("unroll") for (int k = 0; k < 2; ++k) dst[n][k] = *(const PG8_LAS bf16x8*)(lds + PG8_SB(b, h) + boff + n * 2048 + k * 1024); } while (0)
; #define PG8_MMA(ai, bj, At, Bt) do { __builtin_amdgcn_s_setprio(1); _Pragma("unroll") for (int m = 0; m < 4; ++m) _Pragma("unroll") for (int n = 0; n < 2; ++n) _Pragma("unroll") for (int k = 0; k < 2; ++k) \
;         acc[ai][bj][m][n] = __builtin_amdgcn_mfma_f32_16x16x32_bf16(Bt[n][k], At[m][k], acc[ai][bj][m][n], 0, 0, 0); __builtin_amdgcn_s_setprio(0); } while (0)
; #define PG8_WAIT_V(n) asm volatile("s_waitcnt vmcnt(" #n ")" ::: "memory")
; #define PG8_WAIT_L(n) asm volatile("s_waitcnt lgkmcnt(" #n ")" ::: "memory")
; #define PG8_BAR __builtin_amdgcn_s_barrier()
; #define PG8_SCHED __builtin_amdgcn_sched_barrier(0)
; template <class Epi, class Sched, bool ALIGN_EPI = false, bool SP2 = false>
; __device__ __forceinline__ void gemm_phase(PG8_LAS unsigned char* lds, const Gemm g, const Sched& S, const Epi& E) {
;     ...
;             PG8_LDB(B0, 0, 0); PG8_LDB(B1, 0, 1); PG8_SCHED; PG8_LDA(At, 0, 0); PG8_STAGE(PG8_SA(1, 1), a1 + hstep, voffA);
;             PG8_WAIT_V(8); PG8_WAIT_L(0); PG8_BAR; PG8_MMA(0, 0, At, B0); PG8_MMA(0, 1, At, B1); PG8_BAR; PG8_SCHED;
;             PG8_LDA(At, 0, 1); PG8_STAGE(PG8_SB(0, 0), b2, voffB); PG8_STAGE(PG8_SB(0, 1), b2 + hstepB, voffB); PG8_STAGE(PG8_SA(0, 0), a2, voffA);
;             PG8_WAIT_V(8); PG8_WAIT_L(0); PG8_BAR; PG8_MMA(1, 0, At, B0); PG8_MMA(1, 1, At, B1); PG8_BAR; PG8_SCHED;
.LBB0_170:
	s_add_u32 s9, s70, s46
	s_addc_u32 s10, s71, s47
	s_add_u32 s9, s9, 0x100
	s_addc_u32 s10, s10, 0
	s_add_u32 s11, s93, s46
	s_addc_u32 s12, s94, s47
	s_add_i32 s13, 0, 0x10000
	s_cmpk_eq_i32 s46, 0xf00
	s_cselect_b32 s85, s4, s10
	s_cselect_b32 s84, s5, s9
	s_cselect_b32 s81, s6, s12
	s_cselect_b32 s80, s7, s11
	s_add_i32 s9, 0, 0x14000
	v_add_u32_e32 v160, s13, v139
	v_add_u32_e32 v178, s9, v139
	ds_read_b128 v[148:151], v160
	ds_read_b128 v[152:155], v160 offset:1024
	ds_read_b128 v[156:159], v160 offset:2048
	ds_read_b128 v[160:163], v160 offset:3072
	ds_read_b128 v[166:169], v178
	ds_read_b128 v[170:173], v178 offset:1024
	ds_read_b128 v[174:177], v178 offset:2048
	ds_read_b128 v[178:181], v178 offset:3072
	v_lshl_add_u64 v[194:195], v[144:145], 0, s[46:47]
	s_add_i32 m0, s1, 0xc000
	ds_read_b128 v[182:185], v165
	ds_read_b128 v[206:209], v165 offset:1024
	ds_read_b128 v[210:213], v165 offset:2048
	ds_read_b128 v[214:217], v165 offset:3072
	ds_read_b128 v[218:221], v165 offset:4096
	ds_read_b128 v[236:239], v165 offset:5120
	ds_read_b128 v[240:243], v165 offset:6144
	ds_read_b128 v[244:247], v165 offset:7168
	global_load_lds_dwordx4 v[194:195], off
	v_lshl_add_u64 v[194:195], v[146:147], 0, s[46:47]
	s_add_i32 m0, s1, 0xe000
	s_nop 0
	global_load_lds_dwordx4 v[194:195], off
	s_waitcnt vmcnt(8)
	s_waitcnt lgkmcnt(0)
	s_barrier
	s_waitcnt lgkmcnt(0)
	v_mfma_f32_16x16x32_bf16 v[126:129], v[148:151], v[182:185], v[126:129]
	v_mfma_f32_16x16x32_bf16 v[122:125], v[156:159], v[182:185], v[122:125]
	v_mfma_f32_16x16x32_bf16 v[118:121], v[148:151], v[210:213], v[118:121]
	v_mfma_f32_16x16x32_bf16 v[114:117], v[156:159], v[210:213], v[114:117]
	v_mfma_f32_16x16x32_bf16 v[110:113], v[148:151], v[218:221], v[110:113]
	v_mfma_f32_16x16x32_bf16 v[106:109], v[156:159], v[218:221], v[106:109]
	v_mfma_f32_16x16x32_bf16 v[102:105], v[148:151], v[240:243], v[102:105]
	v_mfma_f32_16x16x32_bf16 v[98:101], v[156:159], v[240:243], v[98:101]
	v_mfma_f32_16x16x32_bf16 v[126:129], v[152:155], v[206:209], v[126:129]
	v_mfma_f32_16x16x32_bf16 v[122:125], v[160:163], v[206:209], v[122:125]
	v_mfma_f32_16x16x32_bf16 v[118:121], v[152:155], v[214:217], v[118:121]
	v_mfma_f32_16x16x32_bf16 v[114:117], v[160:163], v[214:217], v[114:117]
	v_mfma_f32_16x16x32_bf16 v[110:113], v[152:155], v[236:239], v[110:113]
	v_mfma_f32_16x16x32_bf16 v[106:109], v[160:163], v[236:239], v[106:109]
	v_mfma_f32_16x16x32_bf16 v[102:105], v[152:155], v[244:247], v[102:105]
	v_mfma_f32_16x16x32_bf16 v[98:101], v[160:163], v[244:247], v[98:101]
	v_mfma_f32_16x16x32_bf16 v[94:97], v[166:169], v[182:185], v[94:97]
	v_mfma_f32_16x16x32_bf16 v[90:93], v[174:177], v[182:185], v[90:93]
	v_mfma_f32_16x16x32_bf16 v[86:89], v[166:169], v[210:213], v[86:89]
	v_mfma_f32_16x16x32_bf16 v[82:85], v[174:177], v[210:213], v[82:85]
	v_mfma_f32_16x16x32_bf16 v[78:81], v[166:169], v[218:221], v[78:81]
	v_mfma_f32_16x16x32_bf16 v[74:77], v[174:177], v[218:221], v[74:77]
	v_mfma_f32_16x16x32_bf16 v[70:73], v[166:169], v[240:243], v[70:73]
	v_mfma_f32_16x16x32_bf16 v[66:69], v[174:177], v[240:243], v[66:69]
	v_mfma_f32_16x16x32_bf16 v[94:97], v[170:173], v[206:209], v[94:97]
	v_mfma_f32_16x16x32_bf16 v[90:93], v[178:181], v[206:209], v[90:93]
	v_mfma_f32_16x16x32_bf16 v[86:89], v[170:173], v[214:217], v[86:89]
	v_mfma_f32_16x16x32_bf16 v[82:85], v[178:181], v[214:217], v[82:85]
	v_mfma_f32_16x16x32_bf16 v[78:81], v[170:173], v[236:239], v[78:81]
	v_mfma_f32_16x16x32_bf16 v[74:77], v[178:181], v[236:239], v[74:77]
	v_mfma_f32_16x16x32_bf16 v[70:73], v[170:173], v[244:247], v[70:73]
	v_mfma_f32_16x16x32_bf16 v[66:69], v[178:181], v[244:247], v[66:69]
	s_barrier
	s_add_i32 s10, s13, s0
	v_lshl_add_u64 v[194:195], s[80:81], 0, v[132:133]
	s_mov_b32 m0, s10
	ds_read_b128 v[182:185], v165 offset:16384
	ds_read_b128 v[206:209], v165 offset:17408
	ds_read_b128 v[210:213], v165 offset:18432
	ds_read_b128 v[214:217], v165 offset:19456
	ds_read_b128 v[218:221], v165 offset:20480
	ds_read_b128 v[236:239], v165 offset:21504
	ds_read_b128 v[240:243], v165 offset:22528
	ds_read_b128 v[244:247], v165 offset:23552
	global_load_lds_dwordx4 v[194:195], off
	s_add_i32 m0, s10, 0x2000
	s_add_u32 s10, s80, 0x20000
	v_lshl_add_u64 v[196:197], s[80:81], 0, v[136:137]
	s_addc_u32 s11, s81, 0
	s_add_i32 s9, s9, s0
	global_load_lds_dwordx4 v[196:197], off
	v_lshl_add_u64 v[222:223], s[10:11], 0, v[132:133]
	s_mov_b32 m0, s9
	v_lshl_add_u64 v[234:235], s[84:85], 0, v[134:135]
	global_load_lds_dwordx4 v[222:223], off
	v_lshl_add_u64 v[222:223], s[10:11], 0, v[136:137]
	s_add_i32 m0, s9, 0x2000
	s_nop 0
	global_load_lds_dwordx4 v[222:223], off
	v_lshl_add_u64 v[222:223], s[84:85], 0, v[130:131]
	s_mov_b32 m0, s1
	s_nop 0
	global_load_lds_dwordx4 v[222:223], off
	s_mov_b32 m0, s25
	s_nop 0
	global_load_lds_dwordx4 v[234:235], off
	s_waitcnt vmcnt(8)
	s_waitcnt lgkmcnt(0)
	s_barrier
; #define PG8_STAGE(bufoff, gbase, voff) do { _Pragma("unroll") for (int _i = 0; _i < 2; ++_i) \
;         __builtin_amdgcn_global_load_lds((const unsigned*)((const char*)(gbase) + (voff)[_i]), (PG8_LAS unsigned*)(lds + (bufoff) + ldsw + _i * 8192), 16, 0, 0); } while (0)
; #define PG8_LDA(dst, b, h) do { _Pragma("unroll") for (int m = 0; m < 4; ++m) _Pragma("unroll") for (int k = 0; k < 2; ++k) dst[m][k] = *(const PG8_LAS bf16x8*)(lds + PG8_SA(b, h) + aoff + m * 2048 + k * 1024); } while (0)
; #define PG8_LDB(dst, b, h) do { _Pragma("unroll") for (int n = 0; n < 2; ++n) _Pragma("unroll") for (int k = 0; k < 2; ++k) dst[n][k] = *(const PG8_LAS bf16x8*)(lds + PG8_SB(b, h) + boff + n * 2048 + k * 1024); } while (0)
; #define PG8_MMA(ai, bj, At, Bt) do { __builtin_amdgcn_s_setprio(1); _Pragma("unroll") for (int m = 0; m < 4; ++m) _Pragma("unroll") for (int n = 0; n < 2; ++n) _Pragma("unroll") for (int k = 0; k < 2; ++k) \
;         acc[ai][bj][m][n] = __builtin_amdgcn_mfma_f32_16x16x32_bf16(Bt[n][k], At[m][k], acc[ai][bj][m][n], 0, 0, 0); __builtin_amdgcn_s_setprio(0); } while (0)
; #define PG8_WAIT_V(n) asm volatile("s_waitcnt vmcnt(" #n ")" ::: "memory")
; #define PG8_WAIT_L(n) asm volatile("s_waitcnt lgkmcnt(" #n ")" ::: "memory")
; #define PG8_BAR __builtin_amdgcn_s_barrier()
; #define PG8_SCHED __builtin_amdgcn_sched_barrier(0)
; template <class Epi, class Sched, bool ALIGN_EPI = false, bool SP2 = false>
; __device__ __forceinline__ void gemm_phase(PG8_LAS unsigned char* lds, const Gemm g, const Sched& S, const Epi& E) {
;     ...
;             PG8_WAIT_V(8); PG8_WAIT_L(0); PG8_BAR; PG8_MMA(1, 0, At, B0); PG8_MMA(1, 1, At, B1); PG8_BAR; PG8_SCHED;
;             PG8_LDB(B0, 1, 0); PG8_LDB(B1, 1, 1); PG8_SCHED; PG8_LDA(At, 1, 0); PG8_STAGE(PG8_SA(0, 1), a2 + hstep, voffA);
;             PG8_WAIT_V(8); PG8_WAIT_L(0); PG8_BAR; PG8_MMA(0, 0, At, B0); PG8_MMA(0, 1, At, B1); PG8_BAR; PG8_SCHED;
	s_waitcnt lgkmcnt(0)
	v_mfma_f32_16x16x32_bf16 v[62:65], v[148:151], v[182:185], v[62:65]
	v_mfma_f32_16x16x32_bf16 v[58:61], v[156:159], v[182:185], v[58:61]
	v_mfma_f32_16x16x32_bf16 v[54:57], v[148:151], v[210:213], v[54:57]
	v_mfma_f32_16x16x32_bf16 v[50:53], v[156:159], v[210:213], v[50:53]
	v_mfma_f32_16x16x32_bf16 v[46:49], v[148:151], v[218:221], v[46:49]
	v_mfma_f32_16x16x32_bf16 v[42:45], v[156:159], v[218:221], v[42:45]
	v_mfma_f32_16x16x32_bf16 v[38:41], v[148:151], v[240:243], v[38:41]
	v_mfma_f32_16x16x32_bf16 v[34:37], v[156:159], v[240:243], v[34:37]
	v_mfma_f32_16x16x32_bf16 v[62:65], v[152:155], v[206:209], v[62:65]
	v_mfma_f32_16x16x32_bf16 v[58:61], v[160:163], v[206:209], v[58:61]
	v_mfma_f32_16x16x32_bf16 v[54:57], v[152:155], v[214:217], v[54:57]
	v_mfma_f32_16x16x32_bf16 v[50:53], v[160:163], v[214:217], v[50:53]
	v_mfma_f32_16x16x32_bf16 v[46:49], v[152:155], v[236:239], v[46:49]
	v_mfma_f32_16x16x32_bf16 v[42:45], v[160:163], v[236:239], v[42:45]
	v_mfma_f32_16x16x32_bf16 v[38:41], v[152:155], v[244:247], v[38:41]
	v_mfma_f32_16x16x32_bf16 v[34:37], v[160:163], v[244:247], v[34:37]
	v_mfma_f32_16x16x32_bf16 v[30:33], v[166:169], v[182:185], v[30:33]
	v_mfma_f32_16x16x32_bf16 v[26:29], v[174:177], v[182:185], v[26:29]
	v_mfma_f32_16x16x32_bf16 v[22:25], v[166:169], v[210:213], v[22:25]
	v_mfma_f32_16x16x32_bf16 v[18:21], v[174:177], v[210:213], v[18:21]
	v_mfma_f32_16x16x32_bf16 v[14:17], v[166:169], v[218:221], v[14:17]
	v_mfma_f32_16x16x32_bf16 v[10:13], v[174:177], v[218:221], v[10:13]
	v_mfma_f32_16x16x32_bf16 v[6:9], v[166:169], v[240:243], v[6:9]
	v_mfma_f32_16x16x32_bf16 v[2:5], v[174:177], v[240:243], v[2:5]
	v_mfma_f32_16x16x32_bf16 v[30:33], v[170:173], v[206:209], v[30:33]
	v_mfma_f32_16x16x32_bf16 v[26:29], v[178:181], v[206:209], v[26:29]
	v_mfma_f32_16x16x32_bf16 v[22:25], v[170:173], v[214:217], v[22:25]
	v_mfma_f32_16x16x32_bf16 v[18:21], v[178:181], v[214:217], v[18:21]
	v_mfma_f32_16x16x32_bf16 v[14:17], v[170:173], v[236:239], v[14:17]
	v_mfma_f32_16x16x32_bf16 v[10:13], v[178:181], v[236:239], v[10:13]
	v_mfma_f32_16x16x32_bf16 v[6:9], v[170:173], v[244:247], v[6:9]
	v_mfma_f32_16x16x32_bf16 v[2:5], v[178:181], v[244:247], v[2:5]
	s_barrier
	s_add_i32 s9, 0, 0x18000
	s_add_i32 s12, 0, 0x1c000
	v_add_u32_e32 v160, s9, v139
	v_add_u32_e32 v178, s12, v139
	ds_read_b128 v[148:151], v160
	ds_read_b128 v[152:155], v160 offset:1024
	ds_read_b128 v[156:159], v160 offset:2048
	ds_read_b128 v[160:163], v160 offset:3072
	ds_read_b128 v[166:169], v178
	ds_read_b128 v[170:173], v178 offset:1024
	ds_read_b128 v[174:177], v178 offset:2048
	ds_read_b128 v[178:181], v178 offset:3072
	s_add_u32 s10, s84, 0x80000
	s_addc_u32 s11, s85, 0
	s_mov_b32 m0, s42
	v_lshl_add_u64 v[198:199], s[10:11], 0, v[130:131]
	ds_read_b128 v[182:185], v165 offset:32768
	ds_read_b128 v[206:209], v165 offset:33792
	ds_read_b128 v[210:213], v165 offset:34816
	ds_read_b128 v[214:217], v165 offset:35840
	ds_read_b128 v[218:221], v165 offset:36864
	ds_read_b128 v[236:239], v165 offset:37888
	ds_read_b128 v[240:243], v165 offset:38912
	ds_read_b128 v[244:247], v165 offset:39936
	global_load_lds_dwordx4 v[198:199], off
	v_lshl_add_u64 v[198:199], s[10:11], 0, v[134:135]
	s_mov_b32 m0, s51
	s_nop 0
	global_load_lds_dwordx4 v[198:199], off
	s_waitcnt vmcnt(8)
	s_waitcnt lgkmcnt(0)
	s_barrier
	s_waitcnt lgkmcnt(0)
	v_mfma_f32_16x16x32_bf16 v[126:129], v[148:151], v[182:185], v[126:129]
	v_mfma_f32_16x16x32_bf16 v[122:125], v[156:159], v[182:185], v[122:125]
	v_mfma_f32_16x16x32_bf16 v[118:121], v[148:151], v[210:213], v[118:121]
	v_mfma_f32_16x16x32_bf16 v[114:117], v[156:159], v[210:213], v[114:117]
	v_mfma_f32_16x16x32_bf16 v[110:113], v[148:151], v[218:221], v[110:113]
	v_mfma_f32_16x16x32_bf16 v[106:109], v[156:159], v[218:221], v[106:109]
	v_mfma_f32_16x16x32_bf16 v[102:105], v[148:151], v[240:243], v[102:105]
	v_mfma_f32_16x16x32_bf16 v[98:101], v[156:159], v[240:243], v[98:101]
	v_mfma_f32_16x16x32_bf16 v[126:129], v[152:155], v[206:209], v[126:129]
	v_mfma_f32_16x16x32_bf16 v[122:125], v[160:163], v[206:209], v[122:125]
	v_mfma_f32_16x16x32_bf16 v[118:121], v[152:155], v[214:217], v[118:121]
	v_mfma_f32_16x16x32_bf16 v[114:117], v[160:163], v[214:217], v[114:117]
	v_mfma_f32_16x16x32_bf16 v[110:113], v[152:155], v[236:239], v[110:113]
	v_mfma_f32_16x16x32_bf16 v[106:109], v[160:163], v[236:239], v[106:109]
	v_mfma_f32_16x16x32_bf16 v[102:105], v[152:155], v[244:247], v[102:105]
	v_mfma_f32_16x16x32_bf16 v[98:101], v[160:163], v[244:247], v[98:101]
	v_mfma_f32_16x16x32_bf16 v[94:97], v[166:169], v[182:185], v[94:97]
	v_mfma_f32_16x16x32_bf16 v[90:93], v[174:177], v[182:185], v[90:93]
	v_mfma_f32_16x16x32_bf16 v[86:89], v[166:169], v[210:213], v[86:89]
	v_mfma_f32_16x16x32_bf16 v[82:85], v[174:177], v[210:213], v[82:85]
	v_mfma_f32_16x16x32_bf16 v[78:81], v[166:169], v[218:221], v[78:81]
	v_mfma_f32_16x16x32_bf16 v[74:77], v[174:177], v[218:221], v[74:77]
	v_mfma_f32_16x16x32_bf16 v[70:73], v[166:169], v[240:243], v[70:73]
	v_mfma_f32_16x16x32_bf16 v[66:69], v[174:177], v[240:243], v[66:69]
	v_mfma_f32_16x16x32_bf16 v[94:97], v[170:173], v[206:209], v[94:97]
	v_mfma_f32_16x16x32_bf16 v[90:93], v[178:181], v[206:209], v[90:93]
	v_mfma_f32_16x16x32_bf16 v[86:89], v[170:173], v[214:217], v[86:89]
	v_mfma_f32_16x16x32_bf16 v[82:85], v[178:181], v[214:217], v[82:85]
	v_mfma_f32_16x16x32_bf16 v[78:81], v[170:173], v[236:239], v[78:81]
	v_mfma_f32_16x16x32_bf16 v[74:77], v[178:181], v[236:239], v[74:77]
	v_mfma_f32_16x16x32_bf16 v[70:73], v[170:173], v[244:247], v[70:73]
	v_mfma_f32_16x16x32_bf16 v[66:69], v[178:181], v[244:247], v[66:69]
	s_barrier
; #define PG8_STAGE(bufoff, gbase, voff) do { _Pragma("unroll") for (int _i = 0; _i < 2; ++_i) \
;         __builtin_amdgcn_global_load_lds((const unsigned*)((const char*)(gbase) + (voff)[_i]), (PG8_LAS unsigned*)(lds + (bufoff) + ldsw + _i * 8192), 16, 0, 0); } while (0)
; #define PG8_LDA(dst, b, h) do { _Pragma("unroll") for (int m = 0; m < 4; ++m) _Pragma("unroll") for (int k = 0; k < 2; ++k) dst[m][k] = *(const PG8_LAS bf16x8*)(lds + PG8_SA(b, h) + aoff + m * 2048 + k * 1024); } while (0)
; #define PG8_MMA(ai, bj, At, Bt) do { __builtin_amdgcn_s_setprio(1); _Pragma("unroll") for (int m = 0; m < 4; ++m) _Pragma("unroll") for (int n = 0; n < 2; ++n) _Pragma("unroll") for (int k = 0; k < 2; ++k) \
;         acc[ai][bj][m][n] = __builtin_amdgcn_mfma_f32_16x16x32_bf16(Bt[n][k], At[m][k], acc[ai][bj][m][n], 0, 0, 0); __builtin_amdgcn_s_setprio(0); } while (0)
; #define PG8_WAIT_V(n) asm volatile("s_waitcnt vmcnt(" #n ")" ::: "memory")
; #define PG8_WAIT_L(n) asm volatile("s_waitcnt lgkmcnt(" #n ")" ::: "memory")
; #define PG8_BAR __builtin_amdgcn_s_barrier()
; #define PG8_SCHED __builtin_amdgcn_sched_barrier(0)
; template <class Epi, class Sched, bool ALIGN_EPI = false, bool SP2 = false>
; __device__ __forceinline__ void gemm_phase(PG8_LAS unsigned char* lds, const Gemm g, const Sched& S, const Epi& E) {
;     ...
;             PG8_LDA(At, 1, 1); PG8_STAGE(PG8_SB(1, 0), b3, voffB); PG8_STAGE(PG8_SB(1, 1), b3 + hstepB, voffB); PG8_STAGE(PG8_SA(1, 0), a3, voffA);
;             PG8_WAIT_V(8); PG8_WAIT_L(0); PG8_BAR; PG8_MMA(1, 0, At, B0); PG8_MMA(1, 1, At, B1); PG8_BAR; PG8_SCHED;
;     ...
;         }
;         if constexpr (ALIGN_EPI) { if (wr == 0) PG8_BAR; }
	s_add_i32 s9, s9, s0
	v_lshl_add_u64 v[194:195], v[194:195], 0, s[60:61]
	s_mov_b32 m0, s9
	ds_read_b128 v[182:185], v165 offset:49152
	ds_read_b128 v[206:209], v165 offset:50176
	ds_read_b128 v[210:213], v165 offset:51200
	ds_read_b128 v[214:217], v165 offset:52224
	ds_read_b128 v[218:221], v165 offset:53248
	ds_read_b128 v[236:239], v165 offset:54272
	ds_read_b128 v[240:243], v165 offset:55296
	ds_read_b128 v[244:247], v165 offset:56320
	global_load_lds_dwordx4 v[194:195], off
	s_add_i32 m0, s9, 0x2000
	s_add_u32 s10, s80, 0x20080
	v_lshl_add_u64 v[194:195], v[196:197], 0, s[60:61]
	s_addc_u32 s11, s81, 0
	s_add_i32 s9, s12, s0
	global_load_lds_dwordx4 v[194:195], off
	v_lshl_add_u64 v[194:195], s[10:11], 0, v[132:133]
	s_mov_b32 m0, s9
	s_nop 0
	global_load_lds_dwordx4 v[194:195], off
	v_lshl_add_u64 v[194:195], s[10:11], 0, v[136:137]
	s_add_i32 m0, s9, 0x2000
	s_nop 0
	global_load_lds_dwordx4 v[194:195], off
	v_lshl_add_u64 v[194:195], v[222:223], 0, s[60:61]
	s_mov_b32 m0, s66
	s_nop 0
	global_load_lds_dwordx4 v[194:195], off
	v_lshl_add_u64 v[194:195], v[234:235], 0, s[60:61]
	s_mov_b32 m0, s67
	s_nop 0
	global_load_lds_dwordx4 v[194:195], off
	s_waitcnt vmcnt(8)
	s_waitcnt lgkmcnt(0)
	s_barrier
	s_waitcnt lgkmcnt(0)
	v_mfma_f32_16x16x32_bf16 v[62:65], v[148:151], v[182:185], v[62:65]
	v_mfma_f32_16x16x32_bf16 v[58:61], v[156:159], v[182:185], v[58:61]
	v_mfma_f32_16x16x32_bf16 v[54:57], v[148:151], v[210:213], v[54:57]
	v_mfma_f32_16x16x32_bf16 v[50:53], v[156:159], v[210:213], v[50:53]
	v_mfma_f32_16x16x32_bf16 v[46:49], v[148:151], v[218:221], v[46:49]
	v_mfma_f32_16x16x32_bf16 v[42:45], v[156:159], v[218:221], v[42:45]
	v_mfma_f32_16x16x32_bf16 v[38:41], v[148:151], v[240:243], v[38:41]
	v_mfma_f32_16x16x32_bf16 v[34:37], v[156:159], v[240:243], v[34:37]
	v_mfma_f32_16x16x32_bf16 v[62:65], v[152:155], v[206:209], v[62:65]
	v_mfma_f32_16x16x32_bf16 v[58:61], v[160:163], v[206:209], v[58:61]
	v_mfma_f32_16x16x32_bf16 v[54:57], v[152:155], v[214:217], v[54:57]
	v_mfma_f32_16x16x32_bf16 v[50:53], v[160:163], v[214:217], v[50:53]
	v_mfma_f32_16x16x32_bf16 v[46:49], v[152:155], v[236:239], v[46:49]
	v_mfma_f32_16x16x32_bf16 v[42:45], v[160:163], v[236:239], v[42:45]
	v_mfma_f32_16x16x32_bf16 v[38:41], v[152:155], v[244:247], v[38:41]
	v_mfma_f32_16x16x32_bf16 v[34:37], v[160:163], v[244:247], v[34:37]
	v_mfma_f32_16x16x32_bf16 v[30:33], v[166:169], v[182:185], v[30:33]
	v_mfma_f32_16x16x32_bf16 v[26:29], v[174:177], v[182:185], v[26:29]
	v_mfma_f32_16x16x32_bf16 v[22:25], v[166:169], v[210:213], v[22:25]
	v_mfma_f32_16x16x32_bf16 v[18:21], v[174:177], v[210:213], v[18:21]
	v_mfma_f32_16x16x32_bf16 v[14:17], v[166:169], v[218:221], v[14:17]
	v_mfma_f32_16x16x32_bf16 v[10:13], v[174:177], v[218:221], v[10:13]
	v_mfma_f32_16x16x32_bf16 v[6:9], v[166:169], v[240:243], v[6:9]
	v_mfma_f32_16x16x32_bf16 v[2:5], v[174:177], v[240:243], v[2:5]
	v_mfma_f32_16x16x32_bf16 v[30:33], v[170:173], v[206:209], v[30:33]
	v_mfma_f32_16x16x32_bf16 v[26:29], v[178:181], v[206:209], v[26:29]
	v_mfma_f32_16x16x32_bf16 v[22:25], v[170:173], v[214:217], v[22:25]
	v_mfma_f32_16x16x32_bf16 v[18:21], v[178:181], v[214:217], v[18:21]
	v_mfma_f32_16x16x32_bf16 v[14:17], v[170:173], v[236:239], v[14:17]
	v_mfma_f32_16x16x32_bf16 v[10:13], v[178:181], v[236:239], v[10:13]
	v_mfma_f32_16x16x32_bf16 v[6:9], v[170:173], v[244:247], v[6:9]
	v_mfma_f32_16x16x32_bf16 v[2:5], v[178:181], v[244:247], v[2:5]
	s_barrier
	s_add_i32 s8, s8, 2
	s_add_u32 s46, s46, 0x100
	s_addc_u32 s47, s47, 0
	s_cmp_gt_u32 s8, 29
	s_cbranch_scc0 .LBB0_170
	s_and_b64 vcc, exec, s[54:55]
	s_cbranch_vccz .LBB0_173
	s_barrier

; #define PG8_STAGE(bufoff, gbase, voff) do { _Pragma("unroll") for (int _i = 0; _i < 2; ++_i) \
;         __builtin_amdgcn_global_load_lds((const unsigned*)((const char*)(gbase) + (voff)[_i]), (PG8_LAS unsigned*)(lds + (bufoff) + ldsw + _i * 8192), 16, 0, 0); } while (0)
; #define PG8_LDA(dst, b, h) do { _Pragma("unroll") for (int m = 0; m < 4; ++m) _Pragma("unroll") for (int k = 0; k < 2; ++k) dst[m][k] = *(const PG8_LAS bf16x8*)(lds + PG8_SA(b, h) + aoff + m * 2048 + k * 1024); } while (0)
; #define PG8_LDB(dst, b, h) do { _Pragma("unroll") for (int n = 0; n < 2; ++n) _Pragma("unroll") for (int k = 0; k < 2; ++k) dst[n][k] = *(const PG8_LAS bf16x8*)(lds + PG8_SB(b, h) + boff + n * 2048 + k * 1024); } while (0)
; #define PG8_MMA(ai, bj, At, Bt) do { __builtin_amdgcn_s_setprio(1); _Pragma("unroll") for (int m = 0; m < 4; ++m) _Pragma("unroll") for (int n = 0; n < 2; ++n) _Pragma("unroll") for (int k = 0; k < 2; ++k) \
;         acc[ai][bj][m][n] = __builtin_amdgcn_mfma_f32_16x16x32_bf16(Bt[n][k], At[m][k], acc[ai][bj][m][n], 0, 0, 0); __builtin_amdgcn_s_setprio(0); } while (0)
; #define PG8_WAIT_V(n) asm volatile("s_waitcnt vmcnt(" #n ")" ::: "memory")
; #define PG8_WAIT_L(n) asm volatile("s_waitcnt lgkmcnt(" #n ")" ::: "memory")
; #define PG8_BAR __builtin_amdgcn_s_barrier()
; #define PG8_SCHED __builtin_amdgcn_sched_barrier(0)
; template <class Epi, class Sched, bool ALIGN_EPI = false, bool SP2 = false>
; __device__ __forceinline__ void gemm_phase(PG8_LAS unsigned char* lds, const Gemm g, const Sched& S, const Epi& E) {
;     ...
;             PG8_LDB(B0, 0, 0); PG8_LDB(B1, 0, 1); PG8_SCHED; PG8_LDA(At, 0, 0); PG8_STAGE(PG8_SA(1, 1), a1 + hstep, voffA);
;             PG8_WAIT_V(8); PG8_WAIT_L(0); PG8_BAR; PG8_MMA(0, 0, At, B0); PG8_MMA(0, 1, At, B1); PG8_BAR; PG8_SCHED;
;             PG8_LDA(At, 0, 1); PG8_STAGE(PG8_SB(0, 0), b2, voffB); PG8_STAGE(PG8_SB(0, 1), b2 + hstepB, voffB); PG8_STAGE(PG8_SA(0, 0), a2, voffA);
;             PG8_WAIT_V(8); PG8_WAIT_L(0); PG8_BAR; PG8_MMA(1, 0, At, B0); PG8_MMA(1, 1, At, B1); PG8_BAR; PG8_SCHED;
.LBB0_788:
	s_add_u32 s9, s68, 0xfffe0080
	s_addc_u32 s10, s69, -1
	s_add_i32 s11, 0, 0x10000
	s_cmp_eq_u32 s8, 4
	s_cselect_b32 s77, s36, s10
	s_cselect_b32 s76, s37, s9
	s_cselect_b32 s73, s4, s7
	s_cselect_b32 s72, s5, s6
	s_add_i32 s9, 0, 0x14000
	v_add_u32_e32 v54, s11, v193
	v_add_u32_e32 v150, s9, v193
	ds_read_b128 v[34:37], v54
	ds_read_b128 v[38:41], v54 offset:1024
	ds_read_b128 v[50:53], v54 offset:2048
	ds_read_b128 v[54:57], v54 offset:3072
	ds_read_b128 v[114:117], v150
	ds_read_b128 v[126:129], v150 offset:1024
	ds_read_b128 v[138:141], v150 offset:2048
	ds_read_b128 v[150:153], v150 offset:3072
	v_lshl_add_u64 v[184:185], s[68:69], 0, v[180:181]
	s_add_i32 m0, s66, 0xc000
	ds_read_b128 v[154:157], v217
	ds_read_b128 v[158:161], v217 offset:1024
	ds_read_b128 v[170:173], v217 offset:2048
	ds_read_b128 v[206:209], v217 offset:3072
	ds_read_b128 v[210:213], v217 offset:4096
	ds_read_b128 v[218:221], v217 offset:5120
	ds_read_b128 v[236:239], v217 offset:6144
	ds_read_b128 v[240:243], v217 offset:7168
	global_load_lds_dwordx4 v[184:185], off
	v_lshl_add_u64 v[184:185], s[68:69], 0, v[182:183]
	s_add_i32 m0, s66, 0xe000
	s_nop 0
	global_load_lds_dwordx4 v[184:185], off
	s_waitcnt vmcnt(8)
	s_waitcnt lgkmcnt(0)
	s_barrier
	s_waitcnt lgkmcnt(0)
	v_mfma_f32_16x16x32_bf16 v[166:169], v[34:37], v[154:157], v[166:169]
	v_mfma_f32_16x16x32_bf16 v[162:165], v[50:53], v[154:157], v[162:165]
	v_mfma_f32_16x16x32_bf16 v[134:137], v[34:37], v[170:173], v[134:137]
	v_mfma_f32_16x16x32_bf16 v[130:133], v[50:53], v[170:173], v[130:133]
	v_mfma_f32_16x16x32_bf16 v[110:113], v[34:37], v[210:213], v[110:113]
	v_mfma_f32_16x16x32_bf16 v[106:109], v[50:53], v[210:213], v[106:109]
	v_mfma_f32_16x16x32_bf16 v[94:97], v[34:37], v[236:239], v[94:97]
	v_mfma_f32_16x16x32_bf16 v[90:93], v[50:53], v[236:239], v[90:93]
	v_mfma_f32_16x16x32_bf16 v[166:169], v[38:41], v[158:161], v[166:169]
	v_mfma_f32_16x16x32_bf16 v[162:165], v[54:57], v[158:161], v[162:165]
	v_mfma_f32_16x16x32_bf16 v[134:137], v[38:41], v[206:209], v[134:137]
	v_mfma_f32_16x16x32_bf16 v[130:133], v[54:57], v[206:209], v[130:133]
	v_mfma_f32_16x16x32_bf16 v[110:113], v[38:41], v[218:221], v[110:113]
	v_mfma_f32_16x16x32_bf16 v[106:109], v[54:57], v[218:221], v[106:109]
	v_mfma_f32_16x16x32_bf16 v[94:97], v[38:41], v[240:243], v[94:97]
	v_mfma_f32_16x16x32_bf16 v[90:93], v[54:57], v[240:243], v[90:93]
	v_mfma_f32_16x16x32_bf16 v[146:149], v[114:117], v[154:157], v[146:149]
	v_mfma_f32_16x16x32_bf16 v[142:145], v[138:141], v[154:157], v[142:145]
	v_mfma_f32_16x16x32_bf16 v[122:125], v[114:117], v[170:173], v[122:125]
	v_mfma_f32_16x16x32_bf16 v[118:121], v[138:141], v[170:173], v[118:121]
	v_mfma_f32_16x16x32_bf16 v[102:105], v[114:117], v[210:213], v[102:105]
	v_mfma_f32_16x16x32_bf16 v[98:101], v[138:141], v[210:213], v[98:101]
	v_mfma_f32_16x16x32_bf16 v[86:89], v[114:117], v[236:239], v[86:89]
	v_mfma_f32_16x16x32_bf16 v[82:85], v[138:141], v[236:239], v[82:85]
	v_mfma_f32_16x16x32_bf16 v[146:149], v[126:129], v[158:161], v[146:149]
	v_mfma_f32_16x16x32_bf16 v[142:145], v[150:153], v[158:161], v[142:145]
	v_mfma_f32_16x16x32_bf16 v[122:125], v[126:129], v[206:209], v[122:125]
	v_mfma_f32_16x16x32_bf16 v[118:121], v[150:153], v[206:209], v[118:121]
	v_mfma_f32_16x16x32_bf16 v[102:105], v[126:129], v[218:221], v[102:105]
	v_mfma_f32_16x16x32_bf16 v[98:101], v[150:153], v[218:221], v[98:101]
	v_mfma_f32_16x16x32_bf16 v[86:89], v[126:129], v[240:243], v[86:89]
	v_mfma_f32_16x16x32_bf16 v[82:85], v[150:153], v[240:243], v[82:85]
	s_barrier
	s_add_i32 s10, s11, s25
	v_lshl_add_u64 v[184:185], s[72:73], 0, v[190:191]
	s_mov_b32 m0, s10
	ds_read_b128 v[154:157], v217 offset:16384
	ds_read_b128 v[158:161], v217 offset:17408
	ds_read_b128 v[170:173], v217 offset:18432
	ds_read_b128 v[206:209], v217 offset:19456
	ds_read_b128 v[210:213], v217 offset:20480
	ds_read_b128 v[218:221], v217 offset:21504
	ds_read_b128 v[236:239], v217 offset:22528
	ds_read_b128 v[240:243], v217 offset:23552
	global_load_lds_dwordx4 v[184:185], off
	s_add_i32 m0, s10, 0x2000
	s_add_u32 s10, s72, 0x8000
	v_lshl_add_u64 v[194:195], s[72:73], 0, v[174:175]
	s_addc_u32 s11, s73, 0
	s_add_i32 s9, s9, s25
	global_load_lds_dwordx4 v[194:195], off
	v_lshl_add_u64 v[196:197], s[10:11], 0, v[190:191]
	s_mov_b32 m0, s9
	v_lshl_add_u64 v[198:199], s[76:77], 0, v[176:177]
	global_load_lds_dwordx4 v[196:197], off
	v_lshl_add_u64 v[196:197], s[10:11], 0, v[174:175]
	s_add_i32 m0, s9, 0x2000
	s_nop 0
	global_load_lds_dwordx4 v[196:197], off
	v_lshl_add_u64 v[196:197], s[76:77], 0, v[178:179]
	s_mov_b32 m0, s66
	s_nop 0
	global_load_lds_dwordx4 v[196:197], off
	s_mov_b32 m0, s67
	s_nop 0
	global_load_lds_dwordx4 v[198:199], off
	s_waitcnt vmcnt(8)
	s_waitcnt lgkmcnt(0)
	s_barrier
; #define PG8_STAGE(bufoff, gbase, voff) do { _Pragma("unroll") for (int _i = 0; _i < 2; ++_i) \
;         __builtin_amdgcn_global_load_lds((const unsigned*)((const char*)(gbase) + (voff)[_i]), (PG8_LAS unsigned*)(lds + (bufoff) + ldsw + _i * 8192), 16, 0, 0); } while (0)
; #define PG8_LDA(dst, b, h) do { _Pragma("unroll") for (int m = 0; m < 4; ++m) _Pragma("unroll") for (int k = 0; k < 2; ++k) dst[m][k] = *(const PG8_LAS bf16x8*)(lds + PG8_SA(b, h) + aoff + m * 2048 + k * 1024); } while (0)
; #define PG8_LDB(dst, b, h) do { _Pragma("unroll") for (int n = 0; n < 2; ++n) _Pragma("unroll") for (int k = 0; k < 2; ++k) dst[n][k] = *(const PG8_LAS bf16x8*)(lds + PG8_SB(b, h) + boff + n * 2048 + k * 1024); } while (0)
; #define PG8_MMA(ai, bj, At, Bt) do { __builtin_amdgcn_s_setprio(1); _Pragma("unroll") for (int m = 0; m < 4; ++m) _Pragma("unroll") for (int n = 0; n < 2; ++n) _Pragma("unroll") for (int k = 0; k < 2; ++k) \
;         acc[ai][bj][m][n] = __builtin_amdgcn_mfma_f32_16x16x32_bf16(Bt[n][k], At[m][k], acc[ai][bj][m][n], 0, 0, 0); __builtin_amdgcn_s_setprio(0); } while (0)
; #define PG8_WAIT_V(n) asm volatile("s_waitcnt vmcnt(" #n ")" ::: "memory")
; #define PG8_WAIT_L(n) asm volatile("s_waitcnt lgkmcnt(" #n ")" ::: "memory")
; #define PG8_BAR __builtin_amdgcn_s_barrier()
; #define PG8_SCHED __builtin_amdgcn_sched_barrier(0)
; template <class Epi, class Sched, bool ALIGN_EPI = false, bool SP2 = false>
; __device__ __forceinline__ void gemm_phase(PG8_LAS unsigned char* lds, const Gemm g, const Sched& S, const Epi& E) {
;     ...
;             PG8_WAIT_V(8); PG8_WAIT_L(0); PG8_BAR; PG8_MMA(1, 0, At, B0); PG8_MMA(1, 1, At, B1); PG8_BAR; PG8_SCHED;
;             PG8_LDB(B0, 1, 0); PG8_LDB(B1, 1, 1); PG8_SCHED; PG8_LDA(At, 1, 0); PG8_STAGE(PG8_SA(0, 1), a2 + hstep, voffA);
;             PG8_WAIT_V(8); PG8_WAIT_L(0); PG8_BAR; PG8_MMA(0, 0, At, B0); PG8_MMA(0, 1, At, B1); PG8_BAR; PG8_SCHED;
	s_waitcnt lgkmcnt(0)
	v_mfma_f32_16x16x32_bf16 v[78:81], v[34:37], v[154:157], v[78:81]
	v_mfma_f32_16x16x32_bf16 v[74:77], v[50:53], v[154:157], v[74:77]
	v_mfma_f32_16x16x32_bf16 v[62:65], v[34:37], v[170:173], v[62:65]
	v_mfma_f32_16x16x32_bf16 v[58:61], v[50:53], v[170:173], v[58:61]
	v_mfma_f32_16x16x32_bf16 v[30:33], v[34:37], v[210:213], v[30:33]
	v_mfma_f32_16x16x32_bf16 v[26:29], v[50:53], v[210:213], v[26:29]
	v_mfma_f32_16x16x32_bf16 v[14:17], v[34:37], v[236:239], v[14:17]
	v_mfma_f32_16x16x32_bf16 v[10:13], v[50:53], v[236:239], v[10:13]
	v_mfma_f32_16x16x32_bf16 v[78:81], v[38:41], v[158:161], v[78:81]
	v_mfma_f32_16x16x32_bf16 v[74:77], v[54:57], v[158:161], v[74:77]
	v_mfma_f32_16x16x32_bf16 v[62:65], v[38:41], v[206:209], v[62:65]
	v_mfma_f32_16x16x32_bf16 v[58:61], v[54:57], v[206:209], v[58:61]
	v_mfma_f32_16x16x32_bf16 v[30:33], v[38:41], v[218:221], v[30:33]
	v_mfma_f32_16x16x32_bf16 v[26:29], v[54:57], v[218:221], v[26:29]
	v_mfma_f32_16x16x32_bf16 v[14:17], v[38:41], v[240:243], v[14:17]
	v_mfma_f32_16x16x32_bf16 v[10:13], v[54:57], v[240:243], v[10:13]
	v_mfma_f32_16x16x32_bf16 v[46:49], v[114:117], v[170:173], v[46:49]
	v_mfma_f32_16x16x32_bf16 v[42:45], v[138:141], v[170:173], v[42:45]
	v_mfma_f32_16x16x32_bf16 v[22:25], v[114:117], v[210:213], v[22:25]
	v_mfma_f32_16x16x32_bf16 v[18:21], v[138:141], v[210:213], v[18:21]
	v_mfma_f32_16x16x32_bf16 v[6:9], v[114:117], v[236:239], v[6:9]
	v_mfma_f32_16x16x32_bf16 v[2:5], v[138:141], v[236:239], v[2:5]
	v_mfma_f32_16x16x32_bf16 v[34:37], v[114:117], v[154:157], v[70:73]
	v_mfma_f32_16x16x32_bf16 v[38:41], v[138:141], v[154:157], v[66:69]
	v_mfma_f32_16x16x32_bf16 v[46:49], v[126:129], v[206:209], v[46:49]
	v_mfma_f32_16x16x32_bf16 v[42:45], v[150:153], v[206:209], v[42:45]
	v_mfma_f32_16x16x32_bf16 v[22:25], v[126:129], v[218:221], v[22:25]
	v_mfma_f32_16x16x32_bf16 v[18:21], v[150:153], v[218:221], v[18:21]
	v_mfma_f32_16x16x32_bf16 v[6:9], v[126:129], v[240:243], v[6:9]
	v_mfma_f32_16x16x32_bf16 v[2:5], v[150:153], v[240:243], v[2:5]
	v_mfma_f32_16x16x32_bf16 v[34:37], v[126:129], v[158:161], v[34:37]
	v_mfma_f32_16x16x32_bf16 v[38:41], v[150:153], v[158:161], v[38:41]
	s_barrier
	s_add_i32 s9, 0, 0x18000
	s_add_i32 s12, 0, 0x1c000
	v_add_u32_e32 v70, s9, v193
	v_add_u32_e32 v150, s12, v193
	ds_read_b128 v[50:53], v70
	ds_read_b128 v[54:57], v70 offset:1024
	ds_read_b128 v[66:69], v70 offset:2048
	ds_read_b128 v[70:73], v70 offset:3072
	ds_read_b128 v[114:117], v150
	ds_read_b128 v[126:129], v150 offset:1024
	ds_read_b128 v[138:141], v150 offset:2048
	ds_read_b128 v[150:153], v150 offset:3072
	s_add_u32 s10, s76, 0x20000
	s_addc_u32 s11, s77, 0
	s_mov_b32 m0, s80
	v_lshl_add_u64 v[214:215], s[10:11], 0, v[178:179]
	ds_read_b128 v[154:157], v217 offset:32768
	ds_read_b128 v[158:161], v217 offset:33792
	ds_read_b128 v[170:173], v217 offset:34816
	ds_read_b128 v[206:209], v217 offset:35840
	ds_read_b128 v[210:213], v217 offset:36864
	ds_read_b128 v[218:221], v217 offset:37888
	ds_read_b128 v[236:239], v217 offset:38912
	ds_read_b128 v[240:243], v217 offset:39936
	global_load_lds_dwordx4 v[214:215], off
	v_lshl_add_u64 v[214:215], s[10:11], 0, v[176:177]
	s_mov_b32 m0, s81
	s_nop 0
	global_load_lds_dwordx4 v[214:215], off
	s_waitcnt vmcnt(8)
	s_waitcnt lgkmcnt(0)
	s_barrier
	s_waitcnt lgkmcnt(0)
	v_mfma_f32_16x16x32_bf16 v[166:169], v[50:53], v[154:157], v[166:169]
	v_mfma_f32_16x16x32_bf16 v[162:165], v[66:69], v[154:157], v[162:165]
	v_mfma_f32_16x16x32_bf16 v[134:137], v[50:53], v[170:173], v[134:137]
	v_mfma_f32_16x16x32_bf16 v[130:133], v[66:69], v[170:173], v[130:133]
	v_mfma_f32_16x16x32_bf16 v[110:113], v[50:53], v[210:213], v[110:113]
	v_mfma_f32_16x16x32_bf16 v[106:109], v[66:69], v[210:213], v[106:109]
	v_mfma_f32_16x16x32_bf16 v[94:97], v[50:53], v[236:239], v[94:97]
	v_mfma_f32_16x16x32_bf16 v[90:93], v[66:69], v[236:239], v[90:93]
	v_mfma_f32_16x16x32_bf16 v[166:169], v[54:57], v[158:161], v[166:169]
	v_mfma_f32_16x16x32_bf16 v[162:165], v[70:73], v[158:161], v[162:165]
	v_mfma_f32_16x16x32_bf16 v[134:137], v[54:57], v[206:209], v[134:137]
	v_mfma_f32_16x16x32_bf16 v[130:133], v[70:73], v[206:209], v[130:133]
	v_mfma_f32_16x16x32_bf16 v[110:113], v[54:57], v[218:221], v[110:113]
	v_mfma_f32_16x16x32_bf16 v[106:109], v[70:73], v[218:221], v[106:109]
	v_mfma_f32_16x16x32_bf16 v[94:97], v[54:57], v[240:243], v[94:97]
	v_mfma_f32_16x16x32_bf16 v[90:93], v[70:73], v[240:243], v[90:93]
	v_mfma_f32_16x16x32_bf16 v[146:149], v[114:117], v[154:157], v[146:149]
	v_mfma_f32_16x16x32_bf16 v[142:145], v[138:141], v[154:157], v[142:145]
	v_mfma_f32_16x16x32_bf16 v[122:125], v[114:117], v[170:173], v[122:125]
	v_mfma_f32_16x16x32_bf16 v[118:121], v[138:141], v[170:173], v[118:121]
	v_mfma_f32_16x16x32_bf16 v[102:105], v[114:117], v[210:213], v[102:105]
	v_mfma_f32_16x16x32_bf16 v[98:101], v[138:141], v[210:213], v[98:101]
	v_mfma_f32_16x16x32_bf16 v[86:89], v[114:117], v[236:239], v[86:89]
	v_mfma_f32_16x16x32_bf16 v[82:85], v[138:141], v[236:239], v[82:85]
	v_mfma_f32_16x16x32_bf16 v[146:149], v[126:129], v[158:161], v[146:149]
	v_mfma_f32_16x16x32_bf16 v[142:145], v[150:153], v[158:161], v[142:145]
	v_mfma_f32_16x16x32_bf16 v[122:125], v[126:129], v[206:209], v[122:125]
	v_mfma_f32_16x16x32_bf16 v[118:121], v[150:153], v[206:209], v[118:121]
	v_mfma_f32_16x16x32_bf16 v[102:105], v[126:129], v[218:221], v[102:105]
	v_mfma_f32_16x16x32_bf16 v[98:101], v[150:153], v[218:221], v[98:101]
	v_mfma_f32_16x16x32_bf16 v[86:89], v[126:129], v[240:243], v[86:89]
	v_mfma_f32_16x16x32_bf16 v[82:85], v[150:153], v[240:243], v[82:85]
	s_barrier
; #define PG8_STAGE(bufoff, gbase, voff) do { _Pragma("unroll") for (int _i = 0; _i < 2; ++_i) \
;         __builtin_amdgcn_global_load_lds((const unsigned*)((const char*)(gbase) + (voff)[_i]), (PG8_LAS unsigned*)(lds + (bufoff) + ldsw + _i * 8192), 16, 0, 0); } while (0)
; #define PG8_LDA(dst, b, h) do { _Pragma("unroll") for (int m = 0; m < 4; ++m) _Pragma("unroll") for (int k = 0; k < 2; ++k) dst[m][k] = *(const PG8_LAS bf16x8*)(lds + PG8_SA(b, h) + aoff + m * 2048 + k * 1024); } while (0)
; #define PG8_MMA(ai, bj, At, Bt) do { __builtin_amdgcn_s_setprio(1); _Pragma("unroll") for (int m = 0; m < 4; ++m) _Pragma("unroll") for (int n = 0; n < 2; ++n) _Pragma("unroll") for (int k = 0; k < 2; ++k) \
;         acc[ai][bj][m][n] = __builtin_amdgcn_mfma_f32_16x16x32_bf16(Bt[n][k], At[m][k], acc[ai][bj][m][n], 0, 0, 0); __builtin_amdgcn_s_setprio(0); } while (0)
; #define PG8_WAIT_V(n) asm volatile("s_waitcnt vmcnt(" #n ")" ::: "memory")
; #define PG8_WAIT_L(n) asm volatile("s_waitcnt lgkmcnt(" #n ")" ::: "memory")
; #define PG8_BAR __builtin_amdgcn_s_barrier()
; #define PG8_SCHED __builtin_amdgcn_sched_barrier(0)
; template <class Epi, class Sched, bool ALIGN_EPI = false, bool SP2 = false>
; __device__ __forceinline__ void gemm_phase(PG8_LAS unsigned char* lds, const Gemm g, const Sched& S, const Epi& E) {
;     ...
;             PG8_LDA(At, 1, 1); PG8_STAGE(PG8_SB(1, 0), b3, voffB); PG8_STAGE(PG8_SB(1, 1), b3 + hstepB, voffB); PG8_STAGE(PG8_SA(1, 0), a3, voffA);
;             PG8_WAIT_V(8); PG8_WAIT_L(0); PG8_BAR; PG8_MMA(1, 0, At, B0); PG8_MMA(1, 1, At, B1); PG8_BAR; PG8_SCHED;
;     ...
;         }
;         if constexpr (ALIGN_EPI) { if (wr == 0) PG8_BAR; }
	s_add_i32 s9, s9, s25
	v_lshl_add_u64 v[184:185], v[184:185], 0, s[60:61]
	s_mov_b32 m0, s9
	ds_read_b128 v[154:157], v217 offset:49152
	ds_read_b128 v[158:161], v217 offset:50176
	ds_read_b128 v[170:173], v217 offset:51200
	ds_read_b128 v[206:209], v217 offset:52224
	ds_read_b128 v[210:213], v217 offset:53248
	ds_read_b128 v[218:221], v217 offset:54272
	ds_read_b128 v[236:239], v217 offset:55296
	ds_read_b128 v[240:243], v217 offset:56320
	global_load_lds_dwordx4 v[184:185], off
	s_add_i32 m0, s9, 0x2000
	s_add_u32 s10, s72, 0x8080
	v_lshl_add_u64 v[184:185], v[194:195], 0, s[60:61]
	s_addc_u32 s11, s73, 0
	s_add_i32 s9, s12, s25
	global_load_lds_dwordx4 v[184:185], off
	v_lshl_add_u64 v[184:185], s[10:11], 0, v[190:191]
	s_mov_b32 m0, s9
	s_nop 0
	global_load_lds_dwordx4 v[184:185], off
	v_lshl_add_u64 v[184:185], s[10:11], 0, v[174:175]
	s_add_i32 m0, s9, 0x2000
	s_nop 0
	global_load_lds_dwordx4 v[184:185], off
	v_lshl_add_u64 v[184:185], v[196:197], 0, s[60:61]
	s_mov_b32 m0, s82
	s_nop 0
	global_load_lds_dwordx4 v[184:185], off
	v_lshl_add_u64 v[184:185], v[198:199], 0, s[60:61]
	s_mov_b32 m0, s92
	s_nop 0
	global_load_lds_dwordx4 v[184:185], off
	s_waitcnt vmcnt(8)
	s_waitcnt lgkmcnt(0)
	s_barrier
	s_waitcnt lgkmcnt(0)
	v_mfma_f32_16x16x32_bf16 v[78:81], v[50:53], v[154:157], v[78:81]
	v_mfma_f32_16x16x32_bf16 v[74:77], v[66:69], v[154:157], v[74:77]
	v_mfma_f32_16x16x32_bf16 v[62:65], v[50:53], v[170:173], v[62:65]
	v_mfma_f32_16x16x32_bf16 v[58:61], v[66:69], v[170:173], v[58:61]
	v_mfma_f32_16x16x32_bf16 v[30:33], v[50:53], v[210:213], v[30:33]
	v_mfma_f32_16x16x32_bf16 v[26:29], v[66:69], v[210:213], v[26:29]
	v_mfma_f32_16x16x32_bf16 v[14:17], v[50:53], v[236:239], v[14:17]
	v_mfma_f32_16x16x32_bf16 v[10:13], v[66:69], v[236:239], v[10:13]
	v_mfma_f32_16x16x32_bf16 v[78:81], v[54:57], v[158:161], v[78:81]
	v_mfma_f32_16x16x32_bf16 v[74:77], v[70:73], v[158:161], v[74:77]
	v_mfma_f32_16x16x32_bf16 v[62:65], v[54:57], v[206:209], v[62:65]
	v_mfma_f32_16x16x32_bf16 v[58:61], v[70:73], v[206:209], v[58:61]
	v_mfma_f32_16x16x32_bf16 v[30:33], v[54:57], v[218:221], v[30:33]
	v_mfma_f32_16x16x32_bf16 v[26:29], v[70:73], v[218:221], v[26:29]
	v_mfma_f32_16x16x32_bf16 v[14:17], v[54:57], v[240:243], v[14:17]
	v_mfma_f32_16x16x32_bf16 v[10:13], v[70:73], v[240:243], v[10:13]
	v_mfma_f32_16x16x32_bf16 v[34:37], v[114:117], v[154:157], v[34:37]
	v_mfma_f32_16x16x32_bf16 v[70:73], v[126:129], v[158:161], v[34:37]
	v_mfma_f32_16x16x32_bf16 v[34:37], v[138:141], v[154:157], v[38:41]
	v_mfma_f32_16x16x32_bf16 v[66:69], v[150:153], v[158:161], v[34:37]
	v_mfma_f32_16x16x32_bf16 v[34:37], v[114:117], v[170:173], v[46:49]
	v_mfma_f32_16x16x32_bf16 v[46:49], v[126:129], v[206:209], v[34:37]
	v_mfma_f32_16x16x32_bf16 v[34:37], v[138:141], v[170:173], v[42:45]
	v_mfma_f32_16x16x32_bf16 v[22:25], v[114:117], v[210:213], v[22:25]
	v_mfma_f32_16x16x32_bf16 v[18:21], v[138:141], v[210:213], v[18:21]
	v_mfma_f32_16x16x32_bf16 v[6:9], v[114:117], v[236:239], v[6:9]
	v_mfma_f32_16x16x32_bf16 v[2:5], v[138:141], v[236:239], v[2:5]
	v_mfma_f32_16x16x32_bf16 v[42:45], v[150:153], v[206:209], v[34:37]
	v_mfma_f32_16x16x32_bf16 v[22:25], v[126:129], v[218:221], v[22:25]
	v_mfma_f32_16x16x32_bf16 v[18:21], v[150:153], v[218:221], v[18:21]
	v_mfma_f32_16x16x32_bf16 v[6:9], v[126:129], v[240:243], v[6:9]
	v_mfma_f32_16x16x32_bf16 v[2:5], v[150:153], v[240:243], v[2:5]
	s_barrier
	s_add_i32 s8, s8, 2
	s_add_u32 s68, s68, 0x100
	s_addc_u32 s69, s69, 0
	s_add_u32 s6, s6, 0x100
	s_addc_u32 s7, s7, 0
	s_cmp_gt_u32 s8, 5
	s_cbranch_scc0 .LBB0_788
	s_and_b64 vcc, exec, s[46:47]
	s_cbranch_vccz .LBB0_791
	s_barrier

; #define PG8_STAGE(bufoff, gbase, voff) do { _Pragma("unroll") for (int _i = 0; _i < 2; ++_i) \
;         __builtin_amdgcn_global_load_lds((const unsigned*)((const char*)(gbase) + (voff)[_i]), (PG8_LAS unsigned*)(lds + (bufoff) + ldsw + _i * 8192), 16, 0, 0); } while (0)
; #define PG8_LDA(dst, b, h) do { _Pragma("unroll") for (int m = 0; m < 4; ++m) _Pragma("unroll") for (int k = 0; k < 2; ++k) dst[m][k] = *(const PG8_LAS bf16x8*)(lds + PG8_SA(b, h) + aoff + m * 2048 + k * 1024); } while (0)
; #define PG8_LDB(dst, b, h) do { _Pragma("unroll") for (int n = 0; n < 2; ++n) _Pragma("unroll") for (int k = 0; k < 2; ++k) dst[n][k] = *(const PG8_LAS bf16x8*)(lds + PG8_SB(b, h) + boff + n * 2048 + k * 1024); } while (0)
; #define PG8_MMA(ai, bj, At, Bt) do { __builtin_amdgcn_s_setprio(1); _Pragma("unroll") for (int m = 0; m < 4; ++m) _Pragma("unroll") for (int n = 0; n < 2; ++n) _Pragma("unroll") for (int k = 0; k < 2; ++k) \
;         acc[ai][bj][m][n] = __builtin_amdgcn_mfma_f32_16x16x32_bf16(Bt[n][k], At[m][k], acc[ai][bj][m][n], 0, 0, 0); __builtin_amdgcn_s_setprio(0); } while (0)
; #define PG8_WAIT_V(n) asm volatile("s_waitcnt vmcnt(" #n ")" ::: "memory")
; #define PG8_WAIT_L(n) asm volatile("s_waitcnt lgkmcnt(" #n ")" ::: "memory")
; #define PG8_BAR __builtin_amdgcn_s_barrier()
; #define PG8_SCHED __builtin_amdgcn_sched_barrier(0)
; template <class Epi, class Sched, bool ALIGN_EPI = false, bool SP2 = false>
; __device__ __forceinline__ void gemm_phase(PG8_LAS unsigned char* lds, const Gemm g, const Sched& S, const Epi& E) {
;     ...
;             PG8_LDB(B0, 0, 0); PG8_LDB(B1, 0, 1); PG8_SCHED; PG8_LDA(At, 0, 0); PG8_STAGE(PG8_SA(1, 1), a1 + hstep, voffA);
;             PG8_WAIT_V(8); PG8_WAIT_L(0); PG8_BAR; PG8_MMA(0, 0, At, B0); PG8_MMA(0, 1, At, B1); PG8_BAR; PG8_SCHED;
;             PG8_LDA(At, 0, 1); PG8_STAGE(PG8_SB(0, 0), b2, voffB); PG8_STAGE(PG8_SB(0, 1), b2 + hstepB, voffB); PG8_STAGE(PG8_SA(0, 0), a2, voffA);
;             PG8_WAIT_V(8); PG8_WAIT_L(0); PG8_BAR; PG8_MMA(1, 0, At, B0); PG8_MMA(1, 1, At, B1); PG8_BAR; PG8_SCHED;
.LBB0_927:
	s_add_u32 s9, s38, 0xfff80080
	s_addc_u32 s10, s39, -1
	s_add_i32 s11, 0, 0x10000
	s_cmp_eq_u32 s8, 28
	s_cselect_b32 s95, s36, s10
	s_cselect_b32 s94, s37, s9
	s_cselect_b32 s47, s4, s7
	s_cselect_b32 s46, s5, s6
	s_add_i32 s9, 0, 0x14000
	v_add_u32_e32 v86, s11, v193
	v_add_u32_e32 v158, s9, v193
	ds_read_b128 v[66:69], v86
	ds_read_b128 v[70:73], v86 offset:1024
	ds_read_b128 v[78:81], v86 offset:2048
	ds_read_b128 v[86:89], v86 offset:3072
	ds_read_b128 v[146:149], v158
	ds_read_b128 v[150:153], v158 offset:1024
	ds_read_b128 v[154:157], v158 offset:2048
	ds_read_b128 v[158:161], v158 offset:3072
	v_lshl_add_u64 v[194:195], s[38:39], 0, v[212:213]
	s_add_i32 m0, s66, 0xc000
	ds_read_b128 v[162:165], v236
	ds_read_b128 v[166:169], v236 offset:1024
	ds_read_b128 v[170:173], v236 offset:2048
	ds_read_b128 v[174:177], v236 offset:3072
	ds_read_b128 v[178:181], v236 offset:4096
	ds_read_b128 v[182:185], v236 offset:5120
	ds_read_b128 v[216:219], v236 offset:6144
	ds_read_b128 v[220:223], v236 offset:7168
	global_load_lds_dwordx4 v[194:195], off
	v_lshl_add_u64 v[194:195], s[38:39], 0, v[214:215]
	s_add_i32 m0, s66, 0xe000
	s_nop 0
	global_load_lds_dwordx4 v[194:195], off
	s_waitcnt vmcnt(8)
	s_waitcnt lgkmcnt(0)
	s_barrier
	s_waitcnt lgkmcnt(0)
	v_mfma_f32_16x16x32_bf16 v[142:145], v[66:69], v[162:165], v[142:145]
	v_mfma_f32_16x16x32_bf16 v[138:141], v[78:81], v[162:165], v[138:141]
	v_mfma_f32_16x16x32_bf16 v[126:129], v[66:69], v[170:173], v[126:129]
	v_mfma_f32_16x16x32_bf16 v[122:125], v[78:81], v[170:173], v[122:125]
	v_mfma_f32_16x16x32_bf16 v[110:113], v[66:69], v[178:181], v[110:113]
	v_mfma_f32_16x16x32_bf16 v[106:109], v[78:81], v[178:181], v[106:109]
	v_mfma_f32_16x16x32_bf16 v[94:97], v[66:69], v[216:219], v[94:97]
	v_mfma_f32_16x16x32_bf16 v[90:93], v[78:81], v[216:219], v[90:93]
	v_mfma_f32_16x16x32_bf16 v[142:145], v[70:73], v[166:169], v[142:145]
	v_mfma_f32_16x16x32_bf16 v[138:141], v[86:89], v[166:169], v[138:141]
	v_mfma_f32_16x16x32_bf16 v[126:129], v[70:73], v[174:177], v[126:129]
	v_mfma_f32_16x16x32_bf16 v[122:125], v[86:89], v[174:177], v[122:125]
	v_mfma_f32_16x16x32_bf16 v[110:113], v[70:73], v[182:185], v[110:113]
	v_mfma_f32_16x16x32_bf16 v[106:109], v[86:89], v[182:185], v[106:109]
	v_mfma_f32_16x16x32_bf16 v[94:97], v[70:73], v[220:223], v[94:97]
	v_mfma_f32_16x16x32_bf16 v[90:93], v[86:89], v[220:223], v[90:93]
	v_mfma_f32_16x16x32_bf16 v[134:137], v[146:149], v[162:165], v[134:137]
	v_mfma_f32_16x16x32_bf16 v[130:133], v[154:157], v[162:165], v[130:133]
	v_mfma_f32_16x16x32_bf16 v[118:121], v[146:149], v[170:173], v[118:121]
	v_mfma_f32_16x16x32_bf16 v[114:117], v[154:157], v[170:173], v[114:117]
	v_mfma_f32_16x16x32_bf16 v[102:105], v[146:149], v[178:181], v[102:105]
	v_mfma_f32_16x16x32_bf16 v[98:101], v[154:157], v[178:181], v[98:101]
	v_mfma_f32_16x16x32_bf16 v[82:85], v[146:149], v[216:219], v[82:85]
	v_mfma_f32_16x16x32_bf16 v[74:77], v[154:157], v[216:219], v[74:77]
	v_mfma_f32_16x16x32_bf16 v[134:137], v[150:153], v[166:169], v[134:137]
	v_mfma_f32_16x16x32_bf16 v[130:133], v[158:161], v[166:169], v[130:133]
	v_mfma_f32_16x16x32_bf16 v[118:121], v[150:153], v[174:177], v[118:121]
	v_mfma_f32_16x16x32_bf16 v[114:117], v[158:161], v[174:177], v[114:117]
	v_mfma_f32_16x16x32_bf16 v[102:105], v[150:153], v[182:185], v[102:105]
	v_mfma_f32_16x16x32_bf16 v[98:101], v[158:161], v[182:185], v[98:101]
	v_mfma_f32_16x16x32_bf16 v[82:85], v[150:153], v[220:223], v[82:85]
	v_mfma_f32_16x16x32_bf16 v[74:77], v[158:161], v[220:223], v[74:77]
	s_barrier
	s_add_i32 s10, s11, s25
	v_lshl_add_u64 v[194:195], s[46:47], 0, v[190:191]
	s_mov_b32 m0, s10
	ds_read_b128 v[162:165], v236 offset:16384
	ds_read_b128 v[166:169], v236 offset:17408
	ds_read_b128 v[170:173], v236 offset:18432
	ds_read_b128 v[174:177], v236 offset:19456
	ds_read_b128 v[178:181], v236 offset:20480
	ds_read_b128 v[182:185], v236 offset:21504
	ds_read_b128 v[216:219], v236 offset:22528
	ds_read_b128 v[220:223], v236 offset:23552
	global_load_lds_dwordx4 v[194:195], off
	s_add_i32 m0, s10, 0x2000
	s_add_u32 s10, s46, 0x20000
	v_lshl_add_u64 v[196:197], s[46:47], 0, v[206:207]
	s_addc_u32 s11, s47, 0
	s_add_i32 s9, s9, s25
	global_load_lds_dwordx4 v[196:197], off
	v_lshl_add_u64 v[198:199], s[10:11], 0, v[190:191]
	s_mov_b32 m0, s9
	v_lshl_add_u64 v[238:239], s[94:95], 0, v[208:209]
	global_load_lds_dwordx4 v[198:199], off
	v_lshl_add_u64 v[198:199], s[10:11], 0, v[206:207]
	s_add_i32 m0, s9, 0x2000
	s_nop 0
	global_load_lds_dwordx4 v[198:199], off
	v_lshl_add_u64 v[198:199], s[94:95], 0, v[210:211]
	s_mov_b32 m0, s66
	s_nop 0
	global_load_lds_dwordx4 v[198:199], off
	s_mov_b32 m0, s67
	s_nop 0
	global_load_lds_dwordx4 v[238:239], off
	s_waitcnt vmcnt(8)
	s_waitcnt lgkmcnt(0)
	s_barrier
; #define PG8_STAGE(bufoff, gbase, voff) do { _Pragma("unroll") for (int _i = 0; _i < 2; ++_i) \
;         __builtin_amdgcn_global_load_lds((const unsigned*)((const char*)(gbase) + (voff)[_i]), (PG8_LAS unsigned*)(lds + (bufoff) + ldsw + _i * 8192), 16, 0, 0); } while (0)
; #define PG8_LDA(dst, b, h) do { _Pragma("unroll") for (int m = 0; m < 4; ++m) _Pragma("unroll") for (int k = 0; k < 2; ++k) dst[m][k] = *(const PG8_LAS bf16x8*)(lds + PG8_SA(b, h) + aoff + m * 2048 + k * 1024); } while (0)
; #define PG8_LDB(dst, b, h) do { _Pragma("unroll") for (int n = 0; n < 2; ++n) _Pragma("unroll") for (int k = 0; k < 2; ++k) dst[n][k] = *(const PG8_LAS bf16x8*)(lds + PG8_SB(b, h) + boff + n * 2048 + k * 1024); } while (0)
; #define PG8_MMA(ai, bj, At, Bt) do { __builtin_amdgcn_s_setprio(1); _Pragma("unroll") for (int m = 0; m < 4; ++m) _Pragma("unroll") for (int n = 0; n < 2; ++n) _Pragma("unroll") for (int k = 0; k < 2; ++k) \
;         acc[ai][bj][m][n] = __builtin_amdgcn_mfma_f32_16x16x32_bf16(Bt[n][k], At[m][k], acc[ai][bj][m][n], 0, 0, 0); __builtin_amdgcn_s_setprio(0); } while (0)
; #define PG8_WAIT_V(n) asm volatile("s_waitcnt vmcnt(" #n ")" ::: "memory")
; #define PG8_WAIT_L(n) asm volatile("s_waitcnt lgkmcnt(" #n ")" ::: "memory")
; #define PG8_BAR __builtin_amdgcn_s_barrier()
; #define PG8_SCHED __builtin_amdgcn_sched_barrier(0)
; template <class Epi, class Sched, bool ALIGN_EPI = false, bool SP2 = false>
; __device__ __forceinline__ void gemm_phase(PG8_LAS unsigned char* lds, const Gemm g, const Sched& S, const Epi& E) {
;     ...
;             PG8_WAIT_V(8); PG8_WAIT_L(0); PG8_BAR; PG8_MMA(1, 0, At, B0); PG8_MMA(1, 1, At, B1); PG8_BAR; PG8_SCHED;
;             PG8_LDB(B0, 1, 0); PG8_LDB(B1, 1, 1); PG8_SCHED; PG8_LDA(At, 1, 0); PG8_STAGE(PG8_SA(0, 1), a2 + hstep, voffA);
;             PG8_WAIT_V(8); PG8_WAIT_L(0); PG8_BAR; PG8_MMA(0, 0, At, B0); PG8_MMA(0, 1, At, B1); PG8_BAR; PG8_SCHED;
	s_waitcnt lgkmcnt(0)
	v_mfma_f32_16x16x32_bf16 v[62:65], v[66:69], v[162:165], v[62:65]
	v_mfma_f32_16x16x32_bf16 v[58:61], v[78:81], v[162:165], v[58:61]
	v_mfma_f32_16x16x32_bf16 v[46:49], v[66:69], v[170:173], v[46:49]
	v_mfma_f32_16x16x32_bf16 v[42:45], v[78:81], v[170:173], v[42:45]
	v_mfma_f32_16x16x32_bf16 v[30:33], v[66:69], v[178:181], v[30:33]
	v_mfma_f32_16x16x32_bf16 v[26:29], v[78:81], v[178:181], v[26:29]
	v_mfma_f32_16x16x32_bf16 v[14:17], v[66:69], v[216:219], v[14:17]
	v_mfma_f32_16x16x32_bf16 v[10:13], v[78:81], v[216:219], v[10:13]
	v_mfma_f32_16x16x32_bf16 v[62:65], v[70:73], v[166:169], v[62:65]
	v_mfma_f32_16x16x32_bf16 v[58:61], v[86:89], v[166:169], v[58:61]
	v_mfma_f32_16x16x32_bf16 v[46:49], v[70:73], v[174:177], v[46:49]
	v_mfma_f32_16x16x32_bf16 v[42:45], v[86:89], v[174:177], v[42:45]
	v_mfma_f32_16x16x32_bf16 v[30:33], v[70:73], v[182:185], v[30:33]
	v_mfma_f32_16x16x32_bf16 v[26:29], v[86:89], v[182:185], v[26:29]
	v_mfma_f32_16x16x32_bf16 v[14:17], v[70:73], v[220:223], v[14:17]
	v_mfma_f32_16x16x32_bf16 v[10:13], v[86:89], v[220:223], v[10:13]
	v_mfma_f32_16x16x32_bf16 v[54:57], v[146:149], v[162:165], v[54:57]
	v_mfma_f32_16x16x32_bf16 v[50:53], v[154:157], v[162:165], v[50:53]
	v_mfma_f32_16x16x32_bf16 v[38:41], v[146:149], v[170:173], v[38:41]
	v_mfma_f32_16x16x32_bf16 v[34:37], v[154:157], v[170:173], v[34:37]
	v_mfma_f32_16x16x32_bf16 v[22:25], v[146:149], v[178:181], v[22:25]
	v_mfma_f32_16x16x32_bf16 v[18:21], v[154:157], v[178:181], v[18:21]
	v_mfma_f32_16x16x32_bf16 v[6:9], v[146:149], v[216:219], v[6:9]
	v_mfma_f32_16x16x32_bf16 v[2:5], v[154:157], v[216:219], v[2:5]
	v_mfma_f32_16x16x32_bf16 v[54:57], v[150:153], v[166:169], v[54:57]
	v_mfma_f32_16x16x32_bf16 v[50:53], v[158:161], v[166:169], v[50:53]
	v_mfma_f32_16x16x32_bf16 v[38:41], v[150:153], v[174:177], v[38:41]
	v_mfma_f32_16x16x32_bf16 v[34:37], v[158:161], v[174:177], v[34:37]
	v_mfma_f32_16x16x32_bf16 v[22:25], v[150:153], v[182:185], v[22:25]
	v_mfma_f32_16x16x32_bf16 v[18:21], v[158:161], v[182:185], v[18:21]
	v_mfma_f32_16x16x32_bf16 v[6:9], v[150:153], v[220:223], v[6:9]
	v_mfma_f32_16x16x32_bf16 v[2:5], v[158:161], v[220:223], v[2:5]
	s_barrier
	s_add_i32 s9, 0, 0x18000
	s_add_i32 s12, 0, 0x1c000
	v_add_u32_e32 v86, s9, v193
	v_add_u32_e32 v158, s12, v193
	ds_read_b128 v[66:69], v86
	ds_read_b128 v[70:73], v86 offset:1024
	ds_read_b128 v[78:81], v86 offset:2048
	ds_read_b128 v[86:89], v86 offset:3072
	ds_read_b128 v[146:149], v158
	ds_read_b128 v[150:153], v158 offset:1024
	ds_read_b128 v[154:157], v158 offset:2048
	ds_read_b128 v[158:161], v158 offset:3072
	s_add_u32 s10, s94, 0x80000
	s_addc_u32 s11, s95, 0
	s_mov_b32 m0, s59
	v_lshl_add_u64 v[240:241], s[10:11], 0, v[210:211]
	ds_read_b128 v[162:165], v236 offset:32768
	ds_read_b128 v[166:169], v236 offset:33792
	ds_read_b128 v[170:173], v236 offset:34816
	ds_read_b128 v[174:177], v236 offset:35840
	ds_read_b128 v[178:181], v236 offset:36864
	ds_read_b128 v[182:185], v236 offset:37888
	ds_read_b128 v[216:219], v236 offset:38912
	ds_read_b128 v[220:223], v236 offset:39936
	global_load_lds_dwordx4 v[240:241], off
	v_lshl_add_u64 v[240:241], s[10:11], 0, v[208:209]
	s_mov_b32 m0, s74
	s_nop 0
	global_load_lds_dwordx4 v[240:241], off
	s_waitcnt vmcnt(8)
	s_waitcnt lgkmcnt(0)
	s_barrier
	s_waitcnt lgkmcnt(0)
	v_mfma_f32_16x16x32_bf16 v[142:145], v[66:69], v[162:165], v[142:145]
	v_mfma_f32_16x16x32_bf16 v[138:141], v[78:81], v[162:165], v[138:141]
	v_mfma_f32_16x16x32_bf16 v[126:129], v[66:69], v[170:173], v[126:129]
	v_mfma_f32_16x16x32_bf16 v[122:125], v[78:81], v[170:173], v[122:125]
	v_mfma_f32_16x16x32_bf16 v[110:113], v[66:69], v[178:181], v[110:113]
	v_mfma_f32_16x16x32_bf16 v[106:109], v[78:81], v[178:181], v[106:109]
	v_mfma_f32_16x16x32_bf16 v[94:97], v[66:69], v[216:219], v[94:97]
	v_mfma_f32_16x16x32_bf16 v[90:93], v[78:81], v[216:219], v[90:93]
	v_mfma_f32_16x16x32_bf16 v[142:145], v[70:73], v[166:169], v[142:145]
	v_mfma_f32_16x16x32_bf16 v[138:141], v[86:89], v[166:169], v[138:141]
	v_mfma_f32_16x16x32_bf16 v[126:129], v[70:73], v[174:177], v[126:129]
	v_mfma_f32_16x16x32_bf16 v[122:125], v[86:89], v[174:177], v[122:125]
	v_mfma_f32_16x16x32_bf16 v[110:113], v[70:73], v[182:185], v[110:113]
	v_mfma_f32_16x16x32_bf16 v[106:109], v[86:89], v[182:185], v[106:109]
	v_mfma_f32_16x16x32_bf16 v[94:97], v[70:73], v[220:223], v[94:97]
	v_mfma_f32_16x16x32_bf16 v[90:93], v[86:89], v[220:223], v[90:93]
	v_mfma_f32_16x16x32_bf16 v[134:137], v[146:149], v[162:165], v[134:137]
	v_mfma_f32_16x16x32_bf16 v[130:133], v[154:157], v[162:165], v[130:133]
	v_mfma_f32_16x16x32_bf16 v[118:121], v[146:149], v[170:173], v[118:121]
	v_mfma_f32_16x16x32_bf16 v[114:117], v[154:157], v[170:173], v[114:117]
	v_mfma_f32_16x16x32_bf16 v[102:105], v[146:149], v[178:181], v[102:105]
	v_mfma_f32_16x16x32_bf16 v[98:101], v[154:157], v[178:181], v[98:101]
	v_mfma_f32_16x16x32_bf16 v[82:85], v[146:149], v[216:219], v[82:85]
	v_mfma_f32_16x16x32_bf16 v[74:77], v[154:157], v[216:219], v[74:77]
	v_mfma_f32_16x16x32_bf16 v[134:137], v[150:153], v[166:169], v[134:137]
	v_mfma_f32_16x16x32_bf16 v[130:133], v[158:161], v[166:169], v[130:133]
	v_mfma_f32_16x16x32_bf16 v[118:121], v[150:153], v[174:177], v[118:121]
	v_mfma_f32_16x16x32_bf16 v[114:117], v[158:161], v[174:177], v[114:117]
	v_mfma_f32_16x16x32_bf16 v[102:105], v[150:153], v[182:185], v[102:105]
	v_mfma_f32_16x16x32_bf16 v[98:101], v[158:161], v[182:185], v[98:101]
	v_mfma_f32_16x16x32_bf16 v[82:85], v[150:153], v[220:223], v[82:85]
	v_mfma_f32_16x16x32_bf16 v[74:77], v[158:161], v[220:223], v[74:77]
	s_barrier
; #define PG8_STAGE(bufoff, gbase, voff) do { _Pragma("unroll") for (int _i = 0; _i < 2; ++_i) \
;         __builtin_amdgcn_global_load_lds((const unsigned*)((const char*)(gbase) + (voff)[_i]), (PG8_LAS unsigned*)(lds + (bufoff) + ldsw + _i * 8192), 16, 0, 0); } while (0)
; #define PG8_LDA(dst, b, h) do { _Pragma("unroll") for (int m = 0; m < 4; ++m) _Pragma("unroll") for (int k = 0; k < 2; ++k) dst[m][k] = *(const PG8_LAS bf16x8*)(lds + PG8_SA(b, h) + aoff + m * 2048 + k * 1024); } while (0)
; #define PG8_MMA(ai, bj, At, Bt) do { __builtin_amdgcn_s_setprio(1); _Pragma("unroll") for (int m = 0; m < 4; ++m) _Pragma("unroll") for (int n = 0; n < 2; ++n) _Pragma("unroll") for (int k = 0; k < 2; ++k) \
;         acc[ai][bj][m][n] = __builtin_amdgcn_mfma_f32_16x16x32_bf16(Bt[n][k], At[m][k], acc[ai][bj][m][n], 0, 0, 0); __builtin_amdgcn_s_setprio(0); } while (0)
; #define PG8_WAIT_V(n) asm volatile("s_waitcnt vmcnt(" #n ")" ::: "memory")
; #define PG8_WAIT_L(n) asm volatile("s_waitcnt lgkmcnt(" #n ")" ::: "memory")
; #define PG8_BAR __builtin_amdgcn_s_barrier()
; #define PG8_SCHED __builtin_amdgcn_sched_barrier(0)
; template <class Epi, class Sched, bool ALIGN_EPI = false, bool SP2 = false>
; __device__ __forceinline__ void gemm_phase(PG8_LAS unsigned char* lds, const Gemm g, const Sched& S, const Epi& E) {
;     ...
;             PG8_LDA(At, 1, 1); PG8_STAGE(PG8_SB(1, 0), b3, voffB); PG8_STAGE(PG8_SB(1, 1), b3 + hstepB, voffB); PG8_STAGE(PG8_SA(1, 0), a3, voffA);
;             PG8_WAIT_V(8); PG8_WAIT_L(0); PG8_BAR; PG8_MMA(1, 0, At, B0); PG8_MMA(1, 1, At, B1); PG8_BAR; PG8_SCHED;
;     ...
;         }
;         if constexpr (ALIGN_EPI) { if (wr == 0) PG8_BAR; }
	s_add_i32 s9, s9, s25
	v_lshl_add_u64 v[194:195], v[194:195], 0, s[60:61]
	s_mov_b32 m0, s9
	ds_read_b128 v[162:165], v236 offset:49152
	ds_read_b128 v[166:169], v236 offset:50176
	ds_read_b128 v[170:173], v236 offset:51200
	ds_read_b128 v[174:177], v236 offset:52224
	ds_read_b128 v[178:181], v236 offset:53248
	ds_read_b128 v[182:185], v236 offset:54272
	ds_read_b128 v[216:219], v236 offset:55296
	ds_read_b128 v[220:223], v236 offset:56320
	global_load_lds_dwordx4 v[194:195], off
	s_add_i32 m0, s9, 0x2000
	s_add_u32 s10, s46, 0x20080
	v_lshl_add_u64 v[194:195], v[196:197], 0, s[60:61]
	s_addc_u32 s11, s47, 0
	s_add_i32 s9, s12, s25
	global_load_lds_dwordx4 v[194:195], off
	v_lshl_add_u64 v[194:195], s[10:11], 0, v[190:191]
	s_mov_b32 m0, s9
	s_nop 0
	global_load_lds_dwordx4 v[194:195], off
	v_lshl_add_u64 v[194:195], s[10:11], 0, v[206:207]
	s_add_i32 m0, s9, 0x2000
	s_nop 0
	global_load_lds_dwordx4 v[194:195], off
	v_lshl_add_u64 v[194:195], v[198:199], 0, s[60:61]
	s_mov_b32 m0, s75
	s_nop 0
	global_load_lds_dwordx4 v[194:195], off
	v_lshl_add_u64 v[194:195], v[238:239], 0, s[60:61]
	s_mov_b32 m0, s0
	s_nop 0
	global_load_lds_dwordx4 v[194:195], off
	s_waitcnt vmcnt(8)
	s_waitcnt lgkmcnt(0)
	s_barrier
	s_waitcnt lgkmcnt(0)
	v_mfma_f32_16x16x32_bf16 v[62:65], v[66:69], v[162:165], v[62:65]
	v_mfma_f32_16x16x32_bf16 v[58:61], v[78:81], v[162:165], v[58:61]
	v_mfma_f32_16x16x32_bf16 v[46:49], v[66:69], v[170:173], v[46:49]
	v_mfma_f32_16x16x32_bf16 v[42:45], v[78:81], v[170:173], v[42:45]
	v_mfma_f32_16x16x32_bf16 v[30:33], v[66:69], v[178:181], v[30:33]
	v_mfma_f32_16x16x32_bf16 v[26:29], v[78:81], v[178:181], v[26:29]
	v_mfma_f32_16x16x32_bf16 v[14:17], v[66:69], v[216:219], v[14:17]
	v_mfma_f32_16x16x32_bf16 v[10:13], v[78:81], v[216:219], v[10:13]
	v_mfma_f32_16x16x32_bf16 v[62:65], v[70:73], v[166:169], v[62:65]
	v_mfma_f32_16x16x32_bf16 v[58:61], v[86:89], v[166:169], v[58:61]
	v_mfma_f32_16x16x32_bf16 v[46:49], v[70:73], v[174:177], v[46:49]
	v_mfma_f32_16x16x32_bf16 v[42:45], v[86:89], v[174:177], v[42:45]
	v_mfma_f32_16x16x32_bf16 v[30:33], v[70:73], v[182:185], v[30:33]
	v_mfma_f32_16x16x32_bf16 v[26:29], v[86:89], v[182:185], v[26:29]
	v_mfma_f32_16x16x32_bf16 v[14:17], v[70:73], v[220:223], v[14:17]
	v_mfma_f32_16x16x32_bf16 v[10:13], v[86:89], v[220:223], v[10:13]
	v_mfma_f32_16x16x32_bf16 v[54:57], v[146:149], v[162:165], v[54:57]
	v_mfma_f32_16x16x32_bf16 v[50:53], v[154:157], v[162:165], v[50:53]
	v_mfma_f32_16x16x32_bf16 v[38:41], v[146:149], v[170:173], v[38:41]
	v_mfma_f32_16x16x32_bf16 v[34:37], v[154:157], v[170:173], v[34:37]
	v_mfma_f32_16x16x32_bf16 v[22:25], v[146:149], v[178:181], v[22:25]
	v_mfma_f32_16x16x32_bf16 v[18:21], v[154:157], v[178:181], v[18:21]
	v_mfma_f32_16x16x32_bf16 v[6:9], v[146:149], v[216:219], v[6:9]
	v_mfma_f32_16x16x32_bf16 v[2:5], v[154:157], v[216:219], v[2:5]
	v_mfma_f32_16x16x32_bf16 v[54:57], v[150:153], v[166:169], v[54:57]
	v_mfma_f32_16x16x32_bf16 v[50:53], v[158:161], v[166:169], v[50:53]
	v_mfma_f32_16x16x32_bf16 v[38:41], v[150:153], v[174:177], v[38:41]
	v_mfma_f32_16x16x32_bf16 v[34:37], v[158:161], v[174:177], v[34:37]
	v_mfma_f32_16x16x32_bf16 v[22:25], v[150:153], v[182:185], v[22:25]
	v_mfma_f32_16x16x32_bf16 v[18:21], v[158:161], v[182:185], v[18:21]
	v_mfma_f32_16x16x32_bf16 v[6:9], v[150:153], v[220:223], v[6:9]
	v_mfma_f32_16x16x32_bf16 v[2:5], v[158:161], v[220:223], v[2:5]
	s_barrier
	s_add_i32 s8, s8, 2
	s_add_u32 s38, s38, 0x100
	s_addc_u32 s39, s39, 0
	s_add_u32 s6, s6, 0x100
	s_addc_u32 s7, s7, 0
	s_cmp_gt_u32 s8, 29
	s_cbranch_scc0 .LBB0_927
	s_and_b64 vcc, exec, s[70:71]
	s_cbranch_vccz .LBB0_930
	s_barrier

; #define PG8_STAGE(bufoff, gbase, voff) do { _Pragma("unroll") for (int _i = 0; _i < 2; ++_i) \
;         __builtin_amdgcn_global_load_lds((const unsigned*)((const char*)(gbase) + (voff)[_i]), (PG8_LAS unsigned*)(lds + (bufoff) + ldsw + _i * 8192), 16, 0, 0); } while (0)
; #define PG8_LDA(dst, b, h) do { _Pragma("unroll") for (int m = 0; m < 4; ++m) _Pragma("unroll") for (int k = 0; k < 2; ++k) dst[m][k] = *(const PG8_LAS bf16x8*)(lds + PG8_SA(b, h) + aoff + m * 2048 + k * 1024); } while (0)
; #define PG8_LDB(dst, b, h) do { _Pragma("unroll") for (int n = 0; n < 2; ++n) _Pragma("unroll") for (int k = 0; k < 2; ++k) dst[n][k] = *(const PG8_LAS bf16x8*)(lds + PG8_SB(b, h) + boff + n * 2048 + k * 1024); } while (0)
; #define PG8_MMA(ai, bj, At, Bt) do { __builtin_amdgcn_s_setprio(1); _Pragma("unroll") for (int m = 0; m < 4; ++m) _Pragma("unroll") for (int n = 0; n < 2; ++n) _Pragma("unroll") for (int k = 0; k < 2; ++k) \
;         acc[ai][bj][m][n] = __builtin_amdgcn_mfma_f32_16x16x32_bf16(Bt[n][k], At[m][k], acc[ai][bj][m][n], 0, 0, 0); __builtin_amdgcn_s_setprio(0); } while (0)
; #define PG8_WAIT_V(n) asm volatile("s_waitcnt vmcnt(" #n ")" ::: "memory")
; #define PG8_WAIT_L(n) asm volatile("s_waitcnt lgkmcnt(" #n ")" ::: "memory")
; #define PG8_BAR __builtin_amdgcn_s_barrier()
; #define PG8_SCHED __builtin_amdgcn_sched_barrier(0)
; template <class Epi, class Sched, bool ALIGN_EPI = false, bool SP2 = false>
; __device__ __forceinline__ void gemm_phase(PG8_LAS unsigned char* lds, const Gemm g, const Sched& S, const Epi& E) {
;     ...
;             PG8_LDB(B0, 0, 0); PG8_LDB(B1, 0, 1); PG8_SCHED; PG8_LDA(At, 0, 0); PG8_STAGE(PG8_SA(1, 1), a1 + hstep, voffA);
;             PG8_WAIT_V(8); PG8_WAIT_L(0); PG8_BAR; PG8_MMA(0, 0, At, B0); PG8_MMA(0, 1, At, B1); PG8_BAR; PG8_SCHED;
;             PG8_LDA(At, 0, 1); PG8_STAGE(PG8_SB(0, 0), b2, voffB); PG8_STAGE(PG8_SB(0, 1), b2 + hstepB, voffB); PG8_STAGE(PG8_SA(0, 0), a2, voffA);
;             PG8_WAIT_V(8); PG8_WAIT_L(0); PG8_BAR; PG8_MMA(1, 0, At, B0); PG8_MMA(1, 1, At, B1); PG8_BAR; PG8_SCHED;
.LBB0_1071:
	s_add_u32 s10, s38, 0xffe00080
	s_addc_u32 s11, s39, -1
	s_add_i32 s12, 0, 0x10000
	s_cmpk_eq_i32 s9, 0x7c
	s_cselect_b32 vcc_hi, s97, s11
	s_cselect_b32 vcc_lo, s4, s10
	s_cselect_b32 s47, s5, s8
	s_cselect_b32 s46, s6, s7
	s_add_i32 s13, 0, 0x14000
	v_add_u32_e32 v152, s12, v164
	v_add_u32_e32 v167, s13, v164
	ds_read_b128 v[130:133], v152
	ds_read_b128 v[134:137], v152 offset:1024
	ds_read_b128 v[138:141], v152 offset:2048
	ds_read_b128 v[152:155], v152 offset:3072
	ds_read_b128 v[156:159], v167
	ds_read_b128 v[160:163], v167 offset:1024
	ds_read_b128 v[168:171], v167 offset:2048
	ds_read_b128 v[172:175], v167 offset:3072
	v_lshl_add_u64 v[184:185], s[38:39], 0, v[148:149]
	s_add_i32 m0, s74, 0xc000
	ds_read_b128 v[176:179], v166
	ds_read_b128 v[180:183], v166 offset:1024
	ds_read_b128 v[206:209], v166 offset:2048
	ds_read_b128 v[210:213], v166 offset:3072
	ds_read_b128 v[214:217], v166 offset:4096
	ds_read_b128 v[218:221], v166 offset:5120
	ds_read_b128 v[236:239], v166 offset:6144
	ds_read_b128 v[240:243], v166 offset:7168
	global_load_lds_dwordx4 v[184:185], off
	v_lshl_add_u64 v[184:185], s[38:39], 0, v[150:151]
	s_add_i32 m0, s74, 0xe000
	s_nop 0
	global_load_lds_dwordx4 v[184:185], off
	s_waitcnt vmcnt(8)
	s_waitcnt lgkmcnt(0)
	s_barrier
	s_waitcnt lgkmcnt(0)
	v_mfma_f32_16x16x32_bf16 v[126:129], v[130:133], v[176:179], v[126:129]
	v_mfma_f32_16x16x32_bf16 v[122:125], v[138:141], v[176:179], v[122:125]
	v_mfma_f32_16x16x32_bf16 v[110:113], v[130:133], v[206:209], v[110:113]
	v_mfma_f32_16x16x32_bf16 v[106:109], v[138:141], v[206:209], v[106:109]
	v_mfma_f32_16x16x32_bf16 v[94:97], v[130:133], v[214:217], v[94:97]
	v_mfma_f32_16x16x32_bf16 v[90:93], v[138:141], v[214:217], v[90:93]
	v_mfma_f32_16x16x32_bf16 v[78:81], v[130:133], v[236:239], v[78:81]
	v_mfma_f32_16x16x32_bf16 v[74:77], v[138:141], v[236:239], v[74:77]
	v_mfma_f32_16x16x32_bf16 v[126:129], v[134:137], v[180:183], v[126:129]
	v_mfma_f32_16x16x32_bf16 v[122:125], v[152:155], v[180:183], v[122:125]
	v_mfma_f32_16x16x32_bf16 v[110:113], v[134:137], v[210:213], v[110:113]
	v_mfma_f32_16x16x32_bf16 v[106:109], v[152:155], v[210:213], v[106:109]
	v_mfma_f32_16x16x32_bf16 v[94:97], v[134:137], v[218:221], v[94:97]
	v_mfma_f32_16x16x32_bf16 v[90:93], v[152:155], v[218:221], v[90:93]
	v_mfma_f32_16x16x32_bf16 v[78:81], v[134:137], v[240:243], v[78:81]
	v_mfma_f32_16x16x32_bf16 v[74:77], v[152:155], v[240:243], v[74:77]
	v_mfma_f32_16x16x32_bf16 v[118:121], v[156:159], v[176:179], v[118:121]
	v_mfma_f32_16x16x32_bf16 v[114:117], v[168:171], v[176:179], v[114:117]
	v_mfma_f32_16x16x32_bf16 v[102:105], v[156:159], v[206:209], v[102:105]
	v_mfma_f32_16x16x32_bf16 v[98:101], v[168:171], v[206:209], v[98:101]
	v_mfma_f32_16x16x32_bf16 v[86:89], v[156:159], v[214:217], v[86:89]
	v_mfma_f32_16x16x32_bf16 v[82:85], v[168:171], v[214:217], v[82:85]
	v_mfma_f32_16x16x32_bf16 v[70:73], v[156:159], v[236:239], v[70:73]
	v_mfma_f32_16x16x32_bf16 v[66:69], v[168:171], v[236:239], v[66:69]
	v_mfma_f32_16x16x32_bf16 v[118:121], v[160:163], v[180:183], v[118:121]
	v_mfma_f32_16x16x32_bf16 v[114:117], v[172:175], v[180:183], v[114:117]
	v_mfma_f32_16x16x32_bf16 v[102:105], v[160:163], v[210:213], v[102:105]
	v_mfma_f32_16x16x32_bf16 v[98:101], v[172:175], v[210:213], v[98:101]
	v_mfma_f32_16x16x32_bf16 v[86:89], v[160:163], v[218:221], v[86:89]
	v_mfma_f32_16x16x32_bf16 v[82:85], v[172:175], v[218:221], v[82:85]
	v_mfma_f32_16x16x32_bf16 v[70:73], v[160:163], v[240:243], v[70:73]
	v_mfma_f32_16x16x32_bf16 v[66:69], v[172:175], v[240:243], v[66:69]
	s_barrier
	s_add_i32 s10, s12, s67
	v_lshl_add_u64 v[184:185], s[46:47], 0, v[146:147]
	s_mov_b32 m0, s10
	ds_read_b128 v[176:179], v166 offset:16384
	ds_read_b128 v[180:183], v166 offset:17408
	ds_read_b128 v[206:209], v166 offset:18432
	ds_read_b128 v[210:213], v166 offset:19456
	ds_read_b128 v[214:217], v166 offset:20480
	ds_read_b128 v[218:221], v166 offset:21504
	ds_read_b128 v[236:239], v166 offset:22528
	ds_read_b128 v[240:243], v166 offset:23552
	global_load_lds_dwordx4 v[184:185], off
	s_add_i32 m0, s10, 0x2000
	s_add_u32 s10, s46, 0x80000
	v_lshl_add_u64 v[194:195], s[46:47], 0, v[142:143]
	s_addc_u32 s11, s47, 0
	s_add_i32 s12, s13, s67
	global_load_lds_dwordx4 v[194:195], off
	v_lshl_add_u64 v[196:197], s[10:11], 0, v[146:147]
	s_mov_b32 m0, s12
	v_lshl_add_u64 v[198:199], vcc, 0, v[144:145]
	global_load_lds_dwordx4 v[196:197], off
	v_lshl_add_u64 v[196:197], s[10:11], 0, v[142:143]
	s_add_i32 m0, s12, 0x2000
	s_nop 0
	global_load_lds_dwordx4 v[196:197], off
	v_lshl_add_u64 v[196:197], vcc, 0, v[190:191]
	s_mov_b32 m0, s74
	s_nop 0
	global_load_lds_dwordx4 v[196:197], off
	s_mov_b32 m0, s75
	s_nop 0
	global_load_lds_dwordx4 v[198:199], off
	s_waitcnt vmcnt(8)
	s_waitcnt lgkmcnt(0)
	s_barrier
; #define PG8_STAGE(bufoff, gbase, voff) do { _Pragma("unroll") for (int _i = 0; _i < 2; ++_i) \
;         __builtin_amdgcn_global_load_lds((const unsigned*)((const char*)(gbase) + (voff)[_i]), (PG8_LAS unsigned*)(lds + (bufoff) + ldsw + _i * 8192), 16, 0, 0); } while (0)
; #define PG8_LDA(dst, b, h) do { _Pragma("unroll") for (int m = 0; m < 4; ++m) _Pragma("unroll") for (int k = 0; k < 2; ++k) dst[m][k] = *(const PG8_LAS bf16x8*)(lds + PG8_SA(b, h) + aoff + m * 2048 + k * 1024); } while (0)
; #define PG8_LDB(dst, b, h) do { _Pragma("unroll") for (int n = 0; n < 2; ++n) _Pragma("unroll") for (int k = 0; k < 2; ++k) dst[n][k] = *(const PG8_LAS bf16x8*)(lds + PG8_SB(b, h) + boff + n * 2048 + k * 1024); } while (0)
; #define PG8_MMA(ai, bj, At, Bt) do { __builtin_amdgcn_s_setprio(1); _Pragma("unroll") for (int m = 0; m < 4; ++m) _Pragma("unroll") for (int n = 0; n < 2; ++n) _Pragma("unroll") for (int k = 0; k < 2; ++k) \
;         acc[ai][bj][m][n] = __builtin_amdgcn_mfma_f32_16x16x32_bf16(Bt[n][k], At[m][k], acc[ai][bj][m][n], 0, 0, 0); __builtin_amdgcn_s_setprio(0); } while (0)
; #define PG8_WAIT_V(n) asm volatile("s_waitcnt vmcnt(" #n ")" ::: "memory")
; #define PG8_WAIT_L(n) asm volatile("s_waitcnt lgkmcnt(" #n ")" ::: "memory")
; #define PG8_BAR __builtin_amdgcn_s_barrier()
; #define PG8_SCHED __builtin_amdgcn_sched_barrier(0)
; template <class Epi, class Sched, bool ALIGN_EPI = false, bool SP2 = false>
; __device__ __forceinline__ void gemm_phase(PG8_LAS unsigned char* lds, const Gemm g, const Sched& S, const Epi& E) {
;     ...
;             PG8_WAIT_V(8); PG8_WAIT_L(0); PG8_BAR; PG8_MMA(1, 0, At, B0); PG8_MMA(1, 1, At, B1); PG8_BAR; PG8_SCHED;
;             PG8_LDB(B0, 1, 0); PG8_LDB(B1, 1, 1); PG8_SCHED; PG8_LDA(At, 1, 0); PG8_STAGE(PG8_SA(0, 1), a2 + hstep, voffA);
;             PG8_WAIT_V(8); PG8_WAIT_L(0); PG8_BAR; PG8_MMA(0, 0, At, B0); PG8_MMA(0, 1, At, B1); PG8_BAR; PG8_SCHED;
	s_waitcnt lgkmcnt(0)
	v_mfma_f32_16x16x32_bf16 v[62:65], v[130:133], v[176:179], v[62:65]
	v_mfma_f32_16x16x32_bf16 v[58:61], v[138:141], v[176:179], v[58:61]
	v_mfma_f32_16x16x32_bf16 v[46:49], v[130:133], v[206:209], v[46:49]
	v_mfma_f32_16x16x32_bf16 v[42:45], v[138:141], v[206:209], v[42:45]
	v_mfma_f32_16x16x32_bf16 v[30:33], v[130:133], v[214:217], v[30:33]
	v_mfma_f32_16x16x32_bf16 v[26:29], v[138:141], v[214:217], v[26:29]
	v_mfma_f32_16x16x32_bf16 v[14:17], v[130:133], v[236:239], v[14:17]
	v_mfma_f32_16x16x32_bf16 v[10:13], v[138:141], v[236:239], v[10:13]
	v_mfma_f32_16x16x32_bf16 v[62:65], v[134:137], v[180:183], v[62:65]
	v_mfma_f32_16x16x32_bf16 v[58:61], v[152:155], v[180:183], v[58:61]
	v_mfma_f32_16x16x32_bf16 v[46:49], v[134:137], v[210:213], v[46:49]
	v_mfma_f32_16x16x32_bf16 v[42:45], v[152:155], v[210:213], v[42:45]
	v_mfma_f32_16x16x32_bf16 v[30:33], v[134:137], v[218:221], v[30:33]
	v_mfma_f32_16x16x32_bf16 v[26:29], v[152:155], v[218:221], v[26:29]
	v_mfma_f32_16x16x32_bf16 v[14:17], v[134:137], v[240:243], v[14:17]
	v_mfma_f32_16x16x32_bf16 v[10:13], v[152:155], v[240:243], v[10:13]
	v_mfma_f32_16x16x32_bf16 v[54:57], v[156:159], v[176:179], v[54:57]
	v_mfma_f32_16x16x32_bf16 v[50:53], v[168:171], v[176:179], v[50:53]
	v_mfma_f32_16x16x32_bf16 v[38:41], v[156:159], v[206:209], v[38:41]
	v_mfma_f32_16x16x32_bf16 v[34:37], v[168:171], v[206:209], v[34:37]
	v_mfma_f32_16x16x32_bf16 v[22:25], v[156:159], v[214:217], v[22:25]
	v_mfma_f32_16x16x32_bf16 v[18:21], v[168:171], v[214:217], v[18:21]
	v_mfma_f32_16x16x32_bf16 v[6:9], v[156:159], v[236:239], v[6:9]
	v_mfma_f32_16x16x32_bf16 v[2:5], v[168:171], v[236:239], v[2:5]
	v_mfma_f32_16x16x32_bf16 v[54:57], v[160:163], v[180:183], v[54:57]
	v_mfma_f32_16x16x32_bf16 v[50:53], v[172:175], v[180:183], v[50:53]
	v_mfma_f32_16x16x32_bf16 v[38:41], v[160:163], v[210:213], v[38:41]
	v_mfma_f32_16x16x32_bf16 v[34:37], v[172:175], v[210:213], v[34:37]
	v_mfma_f32_16x16x32_bf16 v[22:25], v[160:163], v[218:221], v[22:25]
	v_mfma_f32_16x16x32_bf16 v[18:21], v[172:175], v[218:221], v[18:21]
	v_mfma_f32_16x16x32_bf16 v[6:9], v[160:163], v[240:243], v[6:9]
	v_mfma_f32_16x16x32_bf16 v[2:5], v[172:175], v[240:243], v[2:5]
	s_barrier
	s_add_i32 s12, 0, 0x18000
	s_add_i32 s13, 0, 0x1c000
	v_add_u32_e32 v152, s12, v164
	v_add_u32_e32 v167, s13, v164
	ds_read_b128 v[130:133], v152
	ds_read_b128 v[134:137], v152 offset:1024
	ds_read_b128 v[138:141], v152 offset:2048
	ds_read_b128 v[152:155], v152 offset:3072
	ds_read_b128 v[156:159], v167
	ds_read_b128 v[160:163], v167 offset:1024
	ds_read_b128 v[168:171], v167 offset:2048
	ds_read_b128 v[172:175], v167 offset:3072
	s_add_u32 s10, vcc_lo, 0x200000
	s_addc_u32 s11, vcc_hi, 0
	s_mov_b32 m0, s86
	v_lshl_add_u64 v[222:223], s[10:11], 0, v[190:191]
	ds_read_b128 v[176:179], v166 offset:32768
	ds_read_b128 v[180:183], v166 offset:33792
	ds_read_b128 v[206:209], v166 offset:34816
	ds_read_b128 v[210:213], v166 offset:35840
	ds_read_b128 v[214:217], v166 offset:36864
	ds_read_b128 v[218:221], v166 offset:37888
	ds_read_b128 v[236:239], v166 offset:38912
	ds_read_b128 v[240:243], v166 offset:39936
	global_load_lds_dwordx4 v[222:223], off
	v_lshl_add_u64 v[222:223], s[10:11], 0, v[144:145]
	s_mov_b32 m0, s87
	s_nop 0
	global_load_lds_dwordx4 v[222:223], off
	s_waitcnt vmcnt(8)
	s_waitcnt lgkmcnt(0)
	s_barrier
	s_waitcnt lgkmcnt(0)
	v_mfma_f32_16x16x32_bf16 v[126:129], v[130:133], v[176:179], v[126:129]
	v_mfma_f32_16x16x32_bf16 v[122:125], v[138:141], v[176:179], v[122:125]
	v_mfma_f32_16x16x32_bf16 v[110:113], v[130:133], v[206:209], v[110:113]
	v_mfma_f32_16x16x32_bf16 v[106:109], v[138:141], v[206:209], v[106:109]
	v_mfma_f32_16x16x32_bf16 v[94:97], v[130:133], v[214:217], v[94:97]
	v_mfma_f32_16x16x32_bf16 v[90:93], v[138:141], v[214:217], v[90:93]
	v_mfma_f32_16x16x32_bf16 v[78:81], v[130:133], v[236:239], v[78:81]
	v_mfma_f32_16x16x32_bf16 v[74:77], v[138:141], v[236:239], v[74:77]
	v_mfma_f32_16x16x32_bf16 v[126:129], v[134:137], v[180:183], v[126:129]
	v_mfma_f32_16x16x32_bf16 v[122:125], v[152:155], v[180:183], v[122:125]
	v_mfma_f32_16x16x32_bf16 v[110:113], v[134:137], v[210:213], v[110:113]
	v_mfma_f32_16x16x32_bf16 v[106:109], v[152:155], v[210:213], v[106:109]
	v_mfma_f32_16x16x32_bf16 v[94:97], v[134:137], v[218:221], v[94:97]
	v_mfma_f32_16x16x32_bf16 v[90:93], v[152:155], v[218:221], v[90:93]
	v_mfma_f32_16x16x32_bf16 v[78:81], v[134:137], v[240:243], v[78:81]
	v_mfma_f32_16x16x32_bf16 v[74:77], v[152:155], v[240:243], v[74:77]
	v_mfma_f32_16x16x32_bf16 v[118:121], v[156:159], v[176:179], v[118:121]
	v_mfma_f32_16x16x32_bf16 v[114:117], v[168:171], v[176:179], v[114:117]
	v_mfma_f32_16x16x32_bf16 v[102:105], v[156:159], v[206:209], v[102:105]
	v_mfma_f32_16x16x32_bf16 v[98:101], v[168:171], v[206:209], v[98:101]
	v_mfma_f32_16x16x32_bf16 v[86:89], v[156:159], v[214:217], v[86:89]
	v_mfma_f32_16x16x32_bf16 v[82:85], v[168:171], v[214:217], v[82:85]
	v_mfma_f32_16x16x32_bf16 v[70:73], v[156:159], v[236:239], v[70:73]
	v_mfma_f32_16x16x32_bf16 v[66:69], v[168:171], v[236:239], v[66:69]
	v_mfma_f32_16x16x32_bf16 v[118:121], v[160:163], v[180:183], v[118:121]
	v_mfma_f32_16x16x32_bf16 v[114:117], v[172:175], v[180:183], v[114:117]
	v_mfma_f32_16x16x32_bf16 v[102:105], v[160:163], v[210:213], v[102:105]
	v_mfma_f32_16x16x32_bf16 v[98:101], v[172:175], v[210:213], v[98:101]
	v_mfma_f32_16x16x32_bf16 v[86:89], v[160:163], v[218:221], v[86:89]
	v_mfma_f32_16x16x32_bf16 v[82:85], v[172:175], v[218:221], v[82:85]
	v_mfma_f32_16x16x32_bf16 v[70:73], v[160:163], v[240:243], v[70:73]
	v_mfma_f32_16x16x32_bf16 v[66:69], v[172:175], v[240:243], v[66:69]
	s_barrier
; #define PG8_STAGE(bufoff, gbase, voff) do { _Pragma("unroll") for (int _i = 0; _i < 2; ++_i) \
;         __builtin_amdgcn_global_load_lds((const unsigned*)((const char*)(gbase) + (voff)[_i]), (PG8_LAS unsigned*)(lds + (bufoff) + ldsw + _i * 8192), 16, 0, 0); } while (0)
; #define PG8_LDA(dst, b, h) do { _Pragma("unroll") for (int m = 0; m < 4; ++m) _Pragma("unroll") for (int k = 0; k < 2; ++k) dst[m][k] = *(const PG8_LAS bf16x8*)(lds + PG8_SA(b, h) + aoff + m * 2048 + k * 1024); } while (0)
; #define PG8_MMA(ai, bj, At, Bt) do { __builtin_amdgcn_s_setprio(1); _Pragma("unroll") for (int m = 0; m < 4; ++m) _Pragma("unroll") for (int n = 0; n < 2; ++n) _Pragma("unroll") for (int k = 0; k < 2; ++k) \
;         acc[ai][bj][m][n] = __builtin_amdgcn_mfma_f32_16x16x32_bf16(Bt[n][k], At[m][k], acc[ai][bj][m][n], 0, 0, 0); __builtin_amdgcn_s_setprio(0); } while (0)
; #define PG8_WAIT_V(n) asm volatile("s_waitcnt vmcnt(" #n ")" ::: "memory")
; #define PG8_WAIT_L(n) asm volatile("s_waitcnt lgkmcnt(" #n ")" ::: "memory")
; #define PG8_BAR __builtin_amdgcn_s_barrier()
; #define PG8_SCHED __builtin_amdgcn_sched_barrier(0)
; template <class Epi, class Sched, bool ALIGN_EPI = false, bool SP2 = false>
; __device__ __forceinline__ void gemm_phase(PG8_LAS unsigned char* lds, const Gemm g, const Sched& S, const Epi& E) {
;     ...
;             PG8_LDA(At, 1, 1); PG8_STAGE(PG8_SB(1, 0), b3, voffB); PG8_STAGE(PG8_SB(1, 1), b3 + hstepB, voffB); PG8_STAGE(PG8_SA(1, 0), a3, voffA);
;             PG8_WAIT_V(8); PG8_WAIT_L(0); PG8_BAR; PG8_MMA(1, 0, At, B0); PG8_MMA(1, 1, At, B1); PG8_BAR; PG8_SCHED;
;     ...
;         }
;         if constexpr (ALIGN_EPI) { if (wr == 0) PG8_BAR; }
	s_add_i32 s10, s12, s67
	v_lshl_add_u64 v[184:185], v[184:185], 0, s[60:61]
	s_mov_b32 m0, s10
	ds_read_b128 v[176:179], v166 offset:49152
	ds_read_b128 v[180:183], v166 offset:50176
	ds_read_b128 v[206:209], v166 offset:51200
	ds_read_b128 v[210:213], v166 offset:52224
	ds_read_b128 v[214:217], v166 offset:53248
	ds_read_b128 v[218:221], v166 offset:54272
	ds_read_b128 v[236:239], v166 offset:55296
	ds_read_b128 v[240:243], v166 offset:56320
	global_load_lds_dwordx4 v[184:185], off
	s_add_i32 m0, s10, 0x2000
	s_add_u32 s10, s46, 0x80080
	v_lshl_add_u64 v[184:185], v[194:195], 0, s[60:61]
	s_addc_u32 s11, s47, 0
	s_add_i32 s12, s13, s67
	global_load_lds_dwordx4 v[184:185], off
	v_lshl_add_u64 v[184:185], s[10:11], 0, v[146:147]
	s_mov_b32 m0, s12
	s_nop 0
	global_load_lds_dwordx4 v[184:185], off
	v_lshl_add_u64 v[184:185], s[10:11], 0, v[142:143]
	s_add_i32 m0, s12, 0x2000
	s_nop 0
	global_load_lds_dwordx4 v[184:185], off
	v_lshl_add_u64 v[184:185], v[196:197], 0, s[60:61]
	s_mov_b32 m0, s82
	s_nop 0
	global_load_lds_dwordx4 v[184:185], off
	v_lshl_add_u64 v[184:185], v[198:199], 0, s[60:61]
	s_mov_b32 m0, s42
	s_nop 0
	global_load_lds_dwordx4 v[184:185], off
	s_waitcnt vmcnt(8)
	s_waitcnt lgkmcnt(0)
	s_barrier
	s_waitcnt lgkmcnt(0)
	v_mfma_f32_16x16x32_bf16 v[62:65], v[130:133], v[176:179], v[62:65]
	v_mfma_f32_16x16x32_bf16 v[58:61], v[138:141], v[176:179], v[58:61]
	v_mfma_f32_16x16x32_bf16 v[46:49], v[130:133], v[206:209], v[46:49]
	v_mfma_f32_16x16x32_bf16 v[42:45], v[138:141], v[206:209], v[42:45]
	v_mfma_f32_16x16x32_bf16 v[30:33], v[130:133], v[214:217], v[30:33]
	v_mfma_f32_16x16x32_bf16 v[26:29], v[138:141], v[214:217], v[26:29]
	v_mfma_f32_16x16x32_bf16 v[14:17], v[130:133], v[236:239], v[14:17]
	v_mfma_f32_16x16x32_bf16 v[10:13], v[138:141], v[236:239], v[10:13]
	v_mfma_f32_16x16x32_bf16 v[62:65], v[134:137], v[180:183], v[62:65]
	v_mfma_f32_16x16x32_bf16 v[58:61], v[152:155], v[180:183], v[58:61]
	v_mfma_f32_16x16x32_bf16 v[46:49], v[134:137], v[210:213], v[46:49]
	v_mfma_f32_16x16x32_bf16 v[42:45], v[152:155], v[210:213], v[42:45]
	v_mfma_f32_16x16x32_bf16 v[30:33], v[134:137], v[218:221], v[30:33]
	v_mfma_f32_16x16x32_bf16 v[26:29], v[152:155], v[218:221], v[26:29]
	v_mfma_f32_16x16x32_bf16 v[14:17], v[134:137], v[240:243], v[14:17]
	v_mfma_f32_16x16x32_bf16 v[10:13], v[152:155], v[240:243], v[10:13]
	v_mfma_f32_16x16x32_bf16 v[54:57], v[156:159], v[176:179], v[54:57]
	v_mfma_f32_16x16x32_bf16 v[50:53], v[168:171], v[176:179], v[50:53]
	v_mfma_f32_16x16x32_bf16 v[38:41], v[156:159], v[206:209], v[38:41]
	v_mfma_f32_16x16x32_bf16 v[34:37], v[168:171], v[206:209], v[34:37]
	v_mfma_f32_16x16x32_bf16 v[22:25], v[156:159], v[214:217], v[22:25]
	v_mfma_f32_16x16x32_bf16 v[18:21], v[168:171], v[214:217], v[18:21]
	v_mfma_f32_16x16x32_bf16 v[6:9], v[156:159], v[236:239], v[6:9]
	v_mfma_f32_16x16x32_bf16 v[2:5], v[168:171], v[236:239], v[2:5]
	v_mfma_f32_16x16x32_bf16 v[54:57], v[160:163], v[180:183], v[54:57]
	v_mfma_f32_16x16x32_bf16 v[50:53], v[172:175], v[180:183], v[50:53]
	v_mfma_f32_16x16x32_bf16 v[38:41], v[160:163], v[210:213], v[38:41]
	v_mfma_f32_16x16x32_bf16 v[34:37], v[172:175], v[210:213], v[34:37]
	v_mfma_f32_16x16x32_bf16 v[22:25], v[160:163], v[218:221], v[22:25]
	v_mfma_f32_16x16x32_bf16 v[18:21], v[172:175], v[218:221], v[18:21]
	v_mfma_f32_16x16x32_bf16 v[6:9], v[160:163], v[240:243], v[6:9]
	v_mfma_f32_16x16x32_bf16 v[2:5], v[172:175], v[240:243], v[2:5]
	s_barrier
	s_add_i32 s9, s9, 2
	s_add_u32 s38, s38, 0x100
	s_addc_u32 s39, s39, 0
	s_add_u32 s7, s7, 0x100
	s_addc_u32 s8, s8, 0
	s_cmpk_gt_u32 s9, 0x7d
	s_cbranch_scc0 .LBB0_1071
	s_and_b64 vcc, exec, s[72:73]
	s_cbranch_vccz .LBB0_1074
	s_barrier

; #define PG8_STAGE(bufoff, gbase, voff) do { _Pragma("unroll") for (int _i = 0; _i < 2; ++_i) \
;         __builtin_amdgcn_global_load_lds((const unsigned*)((const char*)(gbase) + (voff)[_i]), (PG8_LAS unsigned*)(lds + (bufoff) + ldsw + _i * 8192), 16, 0, 0); } while (0)
; #define PG8_LDA(dst, b, h) do { _Pragma("unroll") for (int m = 0; m < 4; ++m) _Pragma("unroll") for (int k = 0; k < 2; ++k) dst[m][k] = *(const PG8_LAS bf16x8*)(lds + PG8_SA(b, h) + aoff + m * 2048 + k * 1024); } while (0)
; #define PG8_LDB(dst, b, h) do { _Pragma("unroll") for (int n = 0; n < 2; ++n) _Pragma("unroll") for (int k = 0; k < 2; ++k) dst[n][k] = *(const PG8_LAS bf16x8*)(lds + PG8_SB(b, h) + boff + n * 2048 + k * 1024); } while (0)
; #define PG8_MMA(ai, bj, At, Bt) do { __builtin_amdgcn_s_setprio(1); _Pragma("unroll") for (int m = 0; m < 4; ++m) _Pragma("unroll") for (int n = 0; n < 2; ++n) _Pragma("unroll") for (int k = 0; k < 2; ++k) \
;         acc[ai][bj][m][n] = __builtin_amdgcn_mfma_f32_16x16x32_bf16(Bt[n][k], At[m][k], acc[ai][bj][m][n], 0, 0, 0); __builtin_amdgcn_s_setprio(0); } while (0)
; #define PG8_WAIT_V(n) asm volatile("s_waitcnt vmcnt(" #n ")" ::: "memory")
; #define PG8_WAIT_L(n) asm volatile("s_waitcnt lgkmcnt(" #n ")" ::: "memory")
; #define PG8_BAR __builtin_amdgcn_s_barrier()
; #define PG8_SCHED __builtin_amdgcn_sched_barrier(0)
; template <class Epi, class Sched, bool ALIGN_EPI = false, bool SP2 = false>
; __device__ __forceinline__ void gemm_phase(PG8_LAS unsigned char* lds, const Gemm g, const Sched& S, const Epi& E) {
;     ...
;             PG8_LDB(B0, 0, 0); PG8_LDB(B1, 0, 1); PG8_SCHED; PG8_LDA(At, 0, 0); PG8_STAGE(PG8_SA(1, 1), a1 + hstep, voffA);
;             PG8_WAIT_V(8); PG8_WAIT_L(0); PG8_BAR; PG8_MMA(0, 0, At, B0); PG8_MMA(0, 1, At, B1); PG8_BAR; PG8_SCHED;
;             PG8_LDA(At, 0, 1); PG8_STAGE(PG8_SB(0, 0), b2, voffB); PG8_STAGE(PG8_SB(0, 1), b2 + hstepB, voffB); PG8_STAGE(PG8_SA(0, 0), a2, voffA);
;             PG8_WAIT_V(8); PG8_WAIT_L(0); PG8_BAR; PG8_MMA(1, 0, At, B0); PG8_MMA(1, 1, At, B1); PG8_BAR; PG8_SCHED;
.LBB0_1233:
	s_add_u32 s9, s68, s80
	s_addc_u32 s10, s69, s81
	s_add_u32 s9, s9, 0x100
	s_addc_u32 s10, s10, 0
	s_add_u32 s11, s36, s80
	s_addc_u32 s12, s37, s81
	s_add_i32 s13, 0, 0x10000
	s_cmpk_eq_i32 s80, 0xf00
	s_cselect_b32 s93, s4, s10
	s_cselect_b32 s92, s5, s9
	v_add_u32_e32 v144, s13, v145
	s_cselect_b32 s85, s6, s12
	s_cselect_b32 s84, s7, s11
	s_add_i32 s9, 0, 0x14000
	ds_read_b128 v[152:155], v144
	ds_read_b128 v[156:159], v144 offset:1024
	ds_read_b128 v[160:163], v144 offset:2048
	ds_read_b128 v[164:167], v144 offset:3072
	v_add_u32_e32 v144, s9, v145
	ds_read_b128 v[168:171], v144
	ds_read_b128 v[172:175], v144 offset:1024
	ds_read_b128 v[176:179], v144 offset:2048
	ds_read_b128 v[180:183], v144 offset:3072
	v_lshl_add_u64 v[184:185], v[140:141], 0, s[80:81]
	s_add_i32 m0, s51, 0xc000
	ds_read_b128 v[206:209], v151
	ds_read_b128 v[210:213], v151 offset:1024
	ds_read_b128 v[214:217], v151 offset:2048
	ds_read_b128 v[218:221], v151 offset:3072
	ds_read_b128 v[236:239], v151 offset:4096
	ds_read_b128 v[240:243], v151 offset:5120
	ds_read_b128 v[244:247], v151 offset:6144
	ds_read_b128 v[194:197], v151 offset:7168
	global_load_lds_dwordx4 v[184:185], off
	v_lshl_add_u64 v[184:185], v[142:143], 0, s[80:81]
	s_add_i32 m0, s51, 0xe000
	s_nop 0
	global_load_lds_dwordx4 v[184:185], off
	s_waitcnt vmcnt(8)
	s_waitcnt lgkmcnt(0)
	s_barrier
	s_waitcnt lgkmcnt(0)
	v_mfma_f32_16x16x32_bf16 v[126:129], v[152:155], v[206:209], v[126:129]
	v_mfma_f32_16x16x32_bf16 v[122:125], v[160:163], v[206:209], v[122:125]
	v_mfma_f32_16x16x32_bf16 v[118:121], v[152:155], v[214:217], v[118:121]
	v_mfma_f32_16x16x32_bf16 v[114:117], v[160:163], v[214:217], v[114:117]
	v_mfma_f32_16x16x32_bf16 v[110:113], v[152:155], v[236:239], v[110:113]
	v_mfma_f32_16x16x32_bf16 v[106:109], v[160:163], v[236:239], v[106:109]
	v_mfma_f32_16x16x32_bf16 v[102:105], v[152:155], v[244:247], v[102:105]
	v_mfma_f32_16x16x32_bf16 v[98:101], v[160:163], v[244:247], v[98:101]
	v_mfma_f32_16x16x32_bf16 v[126:129], v[156:159], v[210:213], v[126:129]
	v_mfma_f32_16x16x32_bf16 v[122:125], v[164:167], v[210:213], v[122:125]
	v_mfma_f32_16x16x32_bf16 v[118:121], v[156:159], v[218:221], v[118:121]
	v_mfma_f32_16x16x32_bf16 v[114:117], v[164:167], v[218:221], v[114:117]
	v_mfma_f32_16x16x32_bf16 v[110:113], v[156:159], v[240:243], v[110:113]
	v_mfma_f32_16x16x32_bf16 v[106:109], v[164:167], v[240:243], v[106:109]
	v_mfma_f32_16x16x32_bf16 v[102:105], v[156:159], v[194:197], v[102:105]
	v_mfma_f32_16x16x32_bf16 v[98:101], v[164:167], v[194:197], v[98:101]
	v_mfma_f32_16x16x32_bf16 v[94:97], v[168:171], v[206:209], v[94:97]
	v_mfma_f32_16x16x32_bf16 v[90:93], v[176:179], v[206:209], v[90:93]
	v_mfma_f32_16x16x32_bf16 v[86:89], v[168:171], v[214:217], v[86:89]
	v_mfma_f32_16x16x32_bf16 v[82:85], v[176:179], v[214:217], v[82:85]
	v_mfma_f32_16x16x32_bf16 v[78:81], v[168:171], v[236:239], v[78:81]
	v_mfma_f32_16x16x32_bf16 v[74:77], v[176:179], v[236:239], v[74:77]
	v_mfma_f32_16x16x32_bf16 v[70:73], v[168:171], v[244:247], v[70:73]
	v_mfma_f32_16x16x32_bf16 v[66:69], v[176:179], v[244:247], v[66:69]
	v_mfma_f32_16x16x32_bf16 v[94:97], v[172:175], v[210:213], v[94:97]
	v_mfma_f32_16x16x32_bf16 v[90:93], v[180:183], v[210:213], v[90:93]
	v_mfma_f32_16x16x32_bf16 v[86:89], v[172:175], v[218:221], v[86:89]
	v_mfma_f32_16x16x32_bf16 v[82:85], v[180:183], v[218:221], v[82:85]
	v_mfma_f32_16x16x32_bf16 v[78:81], v[172:175], v[240:243], v[78:81]
	v_mfma_f32_16x16x32_bf16 v[74:77], v[180:183], v[240:243], v[74:77]
	v_mfma_f32_16x16x32_bf16 v[70:73], v[172:175], v[194:197], v[70:73]
	v_mfma_f32_16x16x32_bf16 v[66:69], v[180:183], v[194:197], v[66:69]
	s_barrier
	s_add_i32 s10, s13, s42
	v_lshl_add_u64 v[184:185], s[84:85], 0, v[130:131]
	s_mov_b32 m0, s10
	ds_read_b128 v[194:197], v151 offset:16384
	ds_read_b128 v[206:209], v151 offset:17408
	ds_read_b128 v[210:213], v151 offset:18432
	ds_read_b128 v[214:217], v151 offset:19456
	ds_read_b128 v[218:221], v151 offset:20480
	ds_read_b128 v[236:239], v151 offset:21504
	ds_read_b128 v[240:243], v151 offset:22528
	ds_read_b128 v[244:247], v151 offset:23552
	global_load_lds_dwordx4 v[184:185], off
	s_add_i32 m0, s10, 0x2000
	s_add_u32 s10, s84, 0x20000
	v_lshl_add_u64 v[198:199], s[84:85], 0, v[134:135]
	s_addc_u32 s11, s85, 0
	s_add_i32 s9, s9, s42
	global_load_lds_dwordx4 v[198:199], off
	v_lshl_add_u64 v[222:223], s[10:11], 0, v[130:131]
	s_mov_b32 m0, s9
	v_lshl_add_u64 v[234:235], s[92:93], 0, v[132:133]
	global_load_lds_dwordx4 v[222:223], off
	v_lshl_add_u64 v[222:223], s[10:11], 0, v[134:135]
	s_add_i32 m0, s9, 0x2000
	s_nop 0
	global_load_lds_dwordx4 v[222:223], off
	v_lshl_add_u64 v[222:223], s[92:93], 0, v[190:191]
	s_mov_b32 m0, s51
	s_nop 0
	global_load_lds_dwordx4 v[222:223], off
	s_mov_b32 m0, s67
	s_nop 0
	global_load_lds_dwordx4 v[234:235], off
	s_waitcnt vmcnt(8)
	s_waitcnt lgkmcnt(0)
	s_barrier
; #define PG8_STAGE(bufoff, gbase, voff) do { _Pragma("unroll") for (int _i = 0; _i < 2; ++_i) \
;         __builtin_amdgcn_global_load_lds((const unsigned*)((const char*)(gbase) + (voff)[_i]), (PG8_LAS unsigned*)(lds + (bufoff) + ldsw + _i * 8192), 16, 0, 0); } while (0)
; #define PG8_LDA(dst, b, h) do { _Pragma("unroll") for (int m = 0; m < 4; ++m) _Pragma("unroll") for (int k = 0; k < 2; ++k) dst[m][k] = *(const PG8_LAS bf16x8*)(lds + PG8_SA(b, h) + aoff + m * 2048 + k * 1024); } while (0)
; #define PG8_LDB(dst, b, h) do { _Pragma("unroll") for (int n = 0; n < 2; ++n) _Pragma("unroll") for (int k = 0; k < 2; ++k) dst[n][k] = *(const PG8_LAS bf16x8*)(lds + PG8_SB(b, h) + boff + n * 2048 + k * 1024); } while (0)
; #define PG8_MMA(ai, bj, At, Bt) do { __builtin_amdgcn_s_setprio(1); _Pragma("unroll") for (int m = 0; m < 4; ++m) _Pragma("unroll") for (int n = 0; n < 2; ++n) _Pragma("unroll") for (int k = 0; k < 2; ++k) \
;         acc[ai][bj][m][n] = __builtin_amdgcn_mfma_f32_16x16x32_bf16(Bt[n][k], At[m][k], acc[ai][bj][m][n], 0, 0, 0); __builtin_amdgcn_s_setprio(0); } while (0)
; #define PG8_WAIT_V(n) asm volatile("s_waitcnt vmcnt(" #n ")" ::: "memory")
; #define PG8_WAIT_L(n) asm volatile("s_waitcnt lgkmcnt(" #n ")" ::: "memory")
; #define PG8_BAR __builtin_amdgcn_s_barrier()
; #define PG8_SCHED __builtin_amdgcn_sched_barrier(0)
; template <class Epi, class Sched, bool ALIGN_EPI = false, bool SP2 = false>
; __device__ __forceinline__ void gemm_phase(PG8_LAS unsigned char* lds, const Gemm g, const Sched& S, const Epi& E) {
;     ...
;             PG8_WAIT_V(8); PG8_WAIT_L(0); PG8_BAR; PG8_MMA(1, 0, At, B0); PG8_MMA(1, 1, At, B1); PG8_BAR; PG8_SCHED;
;             PG8_LDB(B0, 1, 0); PG8_LDB(B1, 1, 1); PG8_SCHED; PG8_LDA(At, 1, 0); PG8_STAGE(PG8_SA(0, 1), a2 + hstep, voffA);
;             PG8_WAIT_V(8); PG8_WAIT_L(0); PG8_BAR; PG8_MMA(0, 0, At, B0); PG8_MMA(0, 1, At, B1); PG8_BAR; PG8_SCHED;
	s_waitcnt lgkmcnt(0)
	v_mfma_f32_16x16x32_bf16 v[62:65], v[152:155], v[194:197], v[62:65]
	v_mfma_f32_16x16x32_bf16 v[58:61], v[160:163], v[194:197], v[58:61]
	v_mfma_f32_16x16x32_bf16 v[54:57], v[152:155], v[210:213], v[54:57]
	v_mfma_f32_16x16x32_bf16 v[50:53], v[160:163], v[210:213], v[50:53]
	v_mfma_f32_16x16x32_bf16 v[46:49], v[152:155], v[218:221], v[46:49]
	v_mfma_f32_16x16x32_bf16 v[42:45], v[160:163], v[218:221], v[42:45]
	v_mfma_f32_16x16x32_bf16 v[38:41], v[152:155], v[240:243], v[38:41]
	v_mfma_f32_16x16x32_bf16 v[34:37], v[160:163], v[240:243], v[34:37]
	v_mfma_f32_16x16x32_bf16 v[62:65], v[156:159], v[206:209], v[62:65]
	v_mfma_f32_16x16x32_bf16 v[58:61], v[164:167], v[206:209], v[58:61]
	v_mfma_f32_16x16x32_bf16 v[54:57], v[156:159], v[214:217], v[54:57]
	v_mfma_f32_16x16x32_bf16 v[50:53], v[164:167], v[214:217], v[50:53]
	v_mfma_f32_16x16x32_bf16 v[46:49], v[156:159], v[236:239], v[46:49]
	v_mfma_f32_16x16x32_bf16 v[42:45], v[164:167], v[236:239], v[42:45]
	v_mfma_f32_16x16x32_bf16 v[38:41], v[156:159], v[244:247], v[38:41]
	v_mfma_f32_16x16x32_bf16 v[34:37], v[164:167], v[244:247], v[34:37]
	v_mfma_f32_16x16x32_bf16 v[30:33], v[168:171], v[194:197], v[30:33]
	v_mfma_f32_16x16x32_bf16 v[26:29], v[176:179], v[194:197], v[26:29]
	v_mfma_f32_16x16x32_bf16 v[22:25], v[168:171], v[210:213], v[22:25]
	v_mfma_f32_16x16x32_bf16 v[18:21], v[176:179], v[210:213], v[18:21]
	v_mfma_f32_16x16x32_bf16 v[14:17], v[168:171], v[218:221], v[14:17]
	v_mfma_f32_16x16x32_bf16 v[10:13], v[176:179], v[218:221], v[10:13]
	v_mfma_f32_16x16x32_bf16 v[6:9], v[168:171], v[240:243], v[6:9]
	v_mfma_f32_16x16x32_bf16 v[2:5], v[176:179], v[240:243], v[2:5]
	v_mfma_f32_16x16x32_bf16 v[30:33], v[172:175], v[206:209], v[30:33]
	v_mfma_f32_16x16x32_bf16 v[26:29], v[180:183], v[206:209], v[26:29]
	v_mfma_f32_16x16x32_bf16 v[22:25], v[172:175], v[214:217], v[22:25]
	v_mfma_f32_16x16x32_bf16 v[18:21], v[180:183], v[214:217], v[18:21]
	v_mfma_f32_16x16x32_bf16 v[14:17], v[172:175], v[236:239], v[14:17]
	v_mfma_f32_16x16x32_bf16 v[10:13], v[180:183], v[236:239], v[10:13]
	v_mfma_f32_16x16x32_bf16 v[6:9], v[172:175], v[244:247], v[6:9]
	v_mfma_f32_16x16x32_bf16 v[2:5], v[180:183], v[244:247], v[2:5]
	s_barrier
	s_add_i32 s9, 0, 0x18000
	v_add_u32_e32 v144, s9, v145
	s_add_i32 s12, 0, 0x1c000
	ds_read_b128 v[152:155], v144
	ds_read_b128 v[156:159], v144 offset:1024
	ds_read_b128 v[160:163], v144 offset:2048
	ds_read_b128 v[164:167], v144 offset:3072
	v_add_u32_e32 v144, s12, v145
	ds_read_b128 v[168:171], v144
	ds_read_b128 v[172:175], v144 offset:1024
	ds_read_b128 v[176:179], v144 offset:2048
	ds_read_b128 v[180:183], v144 offset:3072
	s_add_u32 s10, s92, 0x80000
	s_addc_u32 s11, s93, 0
	s_mov_b32 m0, s74
	v_lshl_add_u64 v[186:187], s[10:11], 0, v[190:191]
	ds_read_b128 v[194:197], v151 offset:32768
	ds_read_b128 v[206:209], v151 offset:33792
	ds_read_b128 v[210:213], v151 offset:34816
	ds_read_b128 v[214:217], v151 offset:35840
	ds_read_b128 v[218:221], v151 offset:36864
	ds_read_b128 v[236:239], v151 offset:37888
	ds_read_b128 v[240:243], v151 offset:38912
	ds_read_b128 v[244:247], v151 offset:39936
	global_load_lds_dwordx4 v[186:187], off
	v_lshl_add_u64 v[186:187], s[10:11], 0, v[132:133]
	s_mov_b32 m0, s75
	s_nop 0
	global_load_lds_dwordx4 v[186:187], off
	s_waitcnt vmcnt(8)
	s_waitcnt lgkmcnt(0)
	s_barrier
	s_waitcnt lgkmcnt(0)
	v_mfma_f32_16x16x32_bf16 v[126:129], v[152:155], v[194:197], v[126:129]
	v_mfma_f32_16x16x32_bf16 v[122:125], v[160:163], v[194:197], v[122:125]
	v_mfma_f32_16x16x32_bf16 v[118:121], v[152:155], v[210:213], v[118:121]
	v_mfma_f32_16x16x32_bf16 v[114:117], v[160:163], v[210:213], v[114:117]
	v_mfma_f32_16x16x32_bf16 v[110:113], v[152:155], v[218:221], v[110:113]
	v_mfma_f32_16x16x32_bf16 v[106:109], v[160:163], v[218:221], v[106:109]
	v_mfma_f32_16x16x32_bf16 v[102:105], v[152:155], v[240:243], v[102:105]
	v_mfma_f32_16x16x32_bf16 v[98:101], v[160:163], v[240:243], v[98:101]
	v_mfma_f32_16x16x32_bf16 v[126:129], v[156:159], v[206:209], v[126:129]
	v_mfma_f32_16x16x32_bf16 v[122:125], v[164:167], v[206:209], v[122:125]
	v_mfma_f32_16x16x32_bf16 v[118:121], v[156:159], v[214:217], v[118:121]
	v_mfma_f32_16x16x32_bf16 v[114:117], v[164:167], v[214:217], v[114:117]
	v_mfma_f32_16x16x32_bf16 v[110:113], v[156:159], v[236:239], v[110:113]
	v_mfma_f32_16x16x32_bf16 v[106:109], v[164:167], v[236:239], v[106:109]
	v_mfma_f32_16x16x32_bf16 v[102:105], v[156:159], v[244:247], v[102:105]
	v_mfma_f32_16x16x32_bf16 v[98:101], v[164:167], v[244:247], v[98:101]
	v_mfma_f32_16x16x32_bf16 v[94:97], v[168:171], v[194:197], v[94:97]
	v_mfma_f32_16x16x32_bf16 v[90:93], v[176:179], v[194:197], v[90:93]
	v_mfma_f32_16x16x32_bf16 v[86:89], v[168:171], v[210:213], v[86:89]
	v_mfma_f32_16x16x32_bf16 v[82:85], v[176:179], v[210:213], v[82:85]
	v_mfma_f32_16x16x32_bf16 v[78:81], v[168:171], v[218:221], v[78:81]
	v_mfma_f32_16x16x32_bf16 v[74:77], v[176:179], v[218:221], v[74:77]
	v_mfma_f32_16x16x32_bf16 v[70:73], v[168:171], v[240:243], v[70:73]
	v_mfma_f32_16x16x32_bf16 v[66:69], v[176:179], v[240:243], v[66:69]
	v_mfma_f32_16x16x32_bf16 v[94:97], v[172:175], v[206:209], v[94:97]
	v_mfma_f32_16x16x32_bf16 v[90:93], v[180:183], v[206:209], v[90:93]
	v_mfma_f32_16x16x32_bf16 v[86:89], v[172:175], v[214:217], v[86:89]
	v_mfma_f32_16x16x32_bf16 v[82:85], v[180:183], v[214:217], v[82:85]
	v_mfma_f32_16x16x32_bf16 v[78:81], v[172:175], v[236:239], v[78:81]
	v_mfma_f32_16x16x32_bf16 v[74:77], v[180:183], v[236:239], v[74:77]
	v_mfma_f32_16x16x32_bf16 v[70:73], v[172:175], v[244:247], v[70:73]
	v_mfma_f32_16x16x32_bf16 v[66:69], v[180:183], v[244:247], v[66:69]
	s_barrier
; #define PG8_STAGE(bufoff, gbase, voff) do { _Pragma("unroll") for (int _i = 0; _i < 2; ++_i) \
;         __builtin_amdgcn_global_load_lds((const unsigned*)((const char*)(gbase) + (voff)[_i]), (PG8_LAS unsigned*)(lds + (bufoff) + ldsw + _i * 8192), 16, 0, 0); } while (0)
; #define PG8_LDA(dst, b, h) do { _Pragma("unroll") for (int m = 0; m < 4; ++m) _Pragma("unroll") for (int k = 0; k < 2; ++k) dst[m][k] = *(const PG8_LAS bf16x8*)(lds + PG8_SA(b, h) + aoff + m * 2048 + k * 1024); } while (0)
; #define PG8_MMA(ai, bj, At, Bt) do { __builtin_amdgcn_s_setprio(1); _Pragma("unroll") for (int m = 0; m < 4; ++m) _Pragma("unroll") for (int n = 0; n < 2; ++n) _Pragma("unroll") for (int k = 0; k < 2; ++k) \
;         acc[ai][bj][m][n] = __builtin_amdgcn_mfma_f32_16x16x32_bf16(Bt[n][k], At[m][k], acc[ai][bj][m][n], 0, 0, 0); __builtin_amdgcn_s_setprio(0); } while (0)
; #define PG8_WAIT_V(n) asm volatile("s_waitcnt vmcnt(" #n ")" ::: "memory")
; #define PG8_WAIT_L(n) asm volatile("s_waitcnt lgkmcnt(" #n ")" ::: "memory")
; #define PG8_BAR __builtin_amdgcn_s_barrier()
; #define PG8_SCHED __builtin_amdgcn_sched_barrier(0)
; template <class Epi, class Sched, bool ALIGN_EPI = false, bool SP2 = false>
; __device__ __forceinline__ void gemm_phase(PG8_LAS unsigned char* lds, const Gemm g, const Sched& S, const Epi& E) {
;     ...
;             PG8_LDA(At, 1, 1); PG8_STAGE(PG8_SB(1, 0), b3, voffB); PG8_STAGE(PG8_SB(1, 1), b3 + hstepB, voffB); PG8_STAGE(PG8_SA(1, 0), a3, voffA);
;             PG8_WAIT_V(8); PG8_WAIT_L(0); PG8_BAR; PG8_MMA(1, 0, At, B0); PG8_MMA(1, 1, At, B1); PG8_BAR; PG8_SCHED;
	s_add_i32 s9, s9, s42
	v_lshl_add_u64 v[184:185], v[184:185], 0, s[60:61]
	s_mov_b32 m0, s9
	ds_read_b128 v[194:197], v151 offset:49152
	ds_read_b128 v[206:209], v151 offset:50176
	ds_read_b128 v[210:213], v151 offset:51200
	ds_read_b128 v[214:217], v151 offset:52224
	ds_read_b128 v[218:221], v151 offset:53248
	ds_read_b128 v[236:239], v151 offset:54272
	ds_read_b128 v[240:243], v151 offset:55296
	ds_read_b128 v[244:247], v151 offset:56320
	global_load_lds_dwordx4 v[184:185], off
	s_add_i32 m0, s9, 0x2000
	s_add_u32 s10, s84, 0x20080
	v_lshl_add_u64 v[184:185], v[198:199], 0, s[60:61]
	s_addc_u32 s11, s85, 0
	s_add_i32 s9, s12, s42
	global_load_lds_dwordx4 v[184:185], off
	v_lshl_add_u64 v[184:185], s[10:11], 0, v[130:131]
	s_mov_b32 m0, s9
	s_nop 0
	global_load_lds_dwordx4 v[184:185], off
	v_lshl_add_u64 v[184:185], s[10:11], 0, v[134:135]
	s_add_i32 m0, s9, 0x2000
	s_nop 0
	global_load_lds_dwordx4 v[184:185], off
	v_lshl_add_u64 v[184:185], v[222:223], 0, s[60:61]
	s_mov_b32 m0, s82
	s_nop 0
	global_load_lds_dwordx4 v[184:185], off
	v_lshl_add_u64 v[184:185], v[234:235], 0, s[60:61]
	s_mov_b32 m0, s86
	s_nop 0
	global_load_lds_dwordx4 v[184:185], off
	s_waitcnt vmcnt(8)
	s_waitcnt lgkmcnt(0)
	s_barrier
	s_waitcnt lgkmcnt(0)
	v_mfma_f32_16x16x32_bf16 v[62:65], v[152:155], v[194:197], v[62:65]
	v_mfma_f32_16x16x32_bf16 v[58:61], v[160:163], v[194:197], v[58:61]
	v_mfma_f32_16x16x32_bf16 v[54:57], v[152:155], v[210:213], v[54:57]
	v_mfma_f32_16x16x32_bf16 v[50:53], v[160:163], v[210:213], v[50:53]
	v_mfma_f32_16x16x32_bf16 v[46:49], v[152:155], v[218:221], v[46:49]
	v_mfma_f32_16x16x32_bf16 v[42:45], v[160:163], v[218:221], v[42:45]
	v_mfma_f32_16x16x32_bf16 v[38:41], v[152:155], v[240:243], v[38:41]
	v_mfma_f32_16x16x32_bf16 v[34:37], v[160:163], v[240:243], v[34:37]
	v_mfma_f32_16x16x32_bf16 v[62:65], v[156:159], v[206:209], v[62:65]
	v_mfma_f32_16x16x32_bf16 v[58:61], v[164:167], v[206:209], v[58:61]
	v_mfma_f32_16x16x32_bf16 v[54:57], v[156:159], v[214:217], v[54:57]
	v_mfma_f32_16x16x32_bf16 v[50:53], v[164:167], v[214:217], v[50:53]
	v_mfma_f32_16x16x32_bf16 v[46:49], v[156:159], v[236:239], v[46:49]
	v_mfma_f32_16x16x32_bf16 v[42:45], v[164:167], v[236:239], v[42:45]
	v_mfma_f32_16x16x32_bf16 v[38:41], v[156:159], v[244:247], v[38:41]
	v_mfma_f32_16x16x32_bf16 v[34:37], v[164:167], v[244:247], v[34:37]
	v_mfma_f32_16x16x32_bf16 v[30:33], v[168:171], v[194:197], v[30:33]
	v_mfma_f32_16x16x32_bf16 v[26:29], v[176:179], v[194:197], v[26:29]
	v_mfma_f32_16x16x32_bf16 v[22:25], v[168:171], v[210:213], v[22:25]
	v_mfma_f32_16x16x32_bf16 v[18:21], v[176:179], v[210:213], v[18:21]
	v_mfma_f32_16x16x32_bf16 v[14:17], v[168:171], v[218:221], v[14:17]
	v_mfma_f32_16x16x32_bf16 v[10:13], v[176:179], v[218:221], v[10:13]
	v_mfma_f32_16x16x32_bf16 v[6:9], v[168:171], v[240:243], v[6:9]
	v_mfma_f32_16x16x32_bf16 v[2:5], v[176:179], v[240:243], v[2:5]
	v_mfma_f32_16x16x32_bf16 v[30:33], v[172:175], v[206:209], v[30:33]
	v_mfma_f32_16x16x32_bf16 v[26:29], v[180:183], v[206:209], v[26:29]
	v_mfma_f32_16x16x32_bf16 v[22:25], v[172:175], v[214:217], v[22:25]
	v_mfma_f32_16x16x32_bf16 v[18:21], v[180:183], v[214:217], v[18:21]
	v_mfma_f32_16x16x32_bf16 v[14:17], v[172:175], v[236:239], v[14:17]
	v_mfma_f32_16x16x32_bf16 v[10:13], v[180:183], v[236:239], v[10:13]
	v_mfma_f32_16x16x32_bf16 v[6:9], v[172:175], v[244:247], v[6:9]
	v_mfma_f32_16x16x32_bf16 v[2:5], v[180:183], v[244:247], v[2:5]
	s_barrier
	s_add_i32 s8, s8, 2
	s_add_u32 s80, s80, 0x100
	s_addc_u32 s81, s81, 0
	s_cmp_gt_u32 s8, 29
	s_cbranch_scc0 .LBB0_1233
	s_and_b64 vcc, exec, s[62:63]
	s_cbranch_vccz .LBB0_1236
	s_barrier
